# prep section B: tap prefetch depth 6 -> 12 loads (6 more staging quads)
# baseline (speedup 1.0000x reference)
.LBB0_212:
	s_and_b64 vcc, exec, s[0:1]
	s_cbranch_vccz .LBB0_446
	s_add_i32 s64, s36, 0xffffff00
	s_and_b32 s15, s36, 31
	s_lshr_b32 s14, s64, 7
	s_bfe_u32 s16, s36, 0x20005
	s_lshl_b32 s18, s15, 6
	s_lshl_b32 s19, s14, 11
	s_barrier
	s_bfe_u32 s68, s64, 0x20005
	s_lshr_b32 s69, s64, 7
	s_and_b32 s70, s64, 31
	v_readlane_b32 s72, v251, 28
	v_readlane_b32 s73, v251, 29
	s_lshl_b32 s71, s68, 9
	s_mul_i32 s74, s69, 0xa00000
	s_lshl_b32 s75, s68, 8
	s_add_u32 s74, s74, s75
	s_add_u32 s74, s74, 0x400
	s_add_u32 s76, s28, s74
	s_addc_u32 s77, s29, 0
	s_add_u32 s72, s72, s71
	s_addc_u32 s73, s73, 0
	s_lshl_b32 s78, s70, 6
	s_sub_u32 s78, s78, 3
	v_lshrrev_b32_e32 v64, 2, v162
	v_and_b32_e32 v65, 3, v162
	v_add_u32_e32 v66, s78, v64
	v_mov_b32_e32 v67, v66
	v_max_i32_e32 v67, 0, v67
	v_mul_u32_u24_e32 v67, 0x1400, v67
	v_lshl_add_u32 v248, v65, 6, v67
	v_add_u32_e32 v67, 1, v66
	v_max_i32_e32 v67, 0, v67
	v_mul_u32_u24_e32 v67, 0x1400, v67
	v_lshl_add_u32 v249, v65, 6, v67
	v_add_u32_e32 v67, 2, v66
	v_max_i32_e32 v67, 0, v67
	v_mul_u32_u24_e32 v67, 0x1400, v67
	v_lshl_add_u32 v253, v65, 6, v67
	v_add_u32_e32 v67, 3, v66
	v_max_i32_e32 v67, 0, v67
	v_mul_u32_u24_e32 v67, 0x1400, v67
	v_lshl_add_u32 v254, v65, 6, v67
	v_lshrrev_b32_e32 v66, 5, v162
	v_and_b32_e32 v67, 31, v162
	v_lshlrev_b32_e32 v68, 11, v66
	v_lshl_add_u32 v68, v67, 4, v68
	v_mul_u32_u24_e32 v69, 0x240, v66
	v_lshrrev_b32_e32 v70, 3, v67
	v_mul_u32_u24_e32 v70, 0x90, v70
	v_and_b32_e32 v71, 7, v67
	v_lshl_add_u32 v70, v71, 4, v70
	v_add_u32_e32 v69, v69, v70
	v_add_u32_e32 v22, 0xc400, v69
	v_cmp_gt_u32_e32 vcc, 0x80, v162
	v_mov_b32_e32 v71, 0x4000
	v_mov_b32_e32 v70, 0x1200
	s_nop 1
	v_cndmask_b32_e32 v71, 0, v71, vcc
	v_cndmask_b32_e32 v70, 0, v70, vcc
	v_add_u32_e32 v69, v68, v71
	v_add_u32_e32 v23, v22, v70
	global_load_dwordx4 v[56:59], v68, s[72:73]
	global_load_dwordx4 v[60:63], v69, s[72:73]
	global_load_dwordx4 v[28:31], v248, s[76:77] offset:0
	global_load_dwordx4 v[32:35], v249, s[76:77] offset:0
	global_load_dwordx4 v[36:39], v253, s[76:77] offset:0
	global_load_dwordx4 v[40:43], v254, s[76:77] offset:0
	global_load_dwordx4 v[44:47], v248, s[76:77] offset:16
	global_load_dwordx4 v[52:55], v249, s[76:77] offset:16
	global_load_dwordx4 v[168:171], v253, s[76:77] offset:16
	global_load_dwordx4 v[172:175], v254, s[76:77] offset:16
	global_load_dwordx4 v[176:179], v248, s[76:77] offset:32
	global_load_dwordx4 v[180:183], v249, s[76:77] offset:32
	global_load_dwordx4 v[198:201], v253, s[76:77] offset:32
	global_load_dwordx4 v[210:213], v254, s[76:77] offset:32
	s_and_saveexec_b64 s[0:1], s[10:11]
	s_cbranch_execz .LBB0_215
	s_or_b32 s17, s18, s19
	v_or_b32_e32 v0, s17, v162
	v_readlane_b32 s68, v251, 8
	v_lshlrev_b32_e32 v0, 3, v0
	v_readlane_b32 s69, v251, 9
	v_readlane_b32 s70, v251, 10
	v_readlane_b32 s71, v251, 11
	v_readlane_b32 s72, v251, 12
	v_readlane_b32 s73, v251, 13
	v_readlane_b32 s74, v251, 14
	v_readlane_b32 s75, v251, 15
	v_readlane_b32 s76, v251, 16
	v_readlane_b32 s77, v251, 17
	v_readlane_b32 s78, v251, 18
	v_readlane_b32 s79, v251, 19
	v_readlane_b32 s80, v251, 20
	v_readlane_b32 s81, v251, 21
	v_readlane_b32 s82, v251, 22
	v_readlane_b32 s83, v251, 23
	v_lshl_add_u64 v[2:3], v[0:1], 2, s[74:75]
	v_readlane_b32 s68, v251, 24
	s_lshl_b32 s8, s16, 2
	v_readlane_b32 s69, v251, 25
	v_readlane_b32 s70, v251, 26
	v_readlane_b32 s71, v251, 27
	v_readlane_b32 s72, v251, 28
	v_readlane_b32 s73, v251, 29
	v_readlane_b32 s74, v251, 30
	v_readlane_b32 s75, v251, 31
	v_lshl_add_u64 v[2:3], v[2:3], 0, s[8:9]
	v_readlane_b32 s76, v251, 32
	v_readlane_b32 s77, v251, 33
	v_readlane_b32 s78, v251, 34
	v_readlane_b32 s79, v251, 35
	s_mov_b64 s[68:69], s[72:73]
	global_load_dword v0, v[2:3], off
	s_mov_b64 s[70:71], s[74:75]
	global_load_dword v2, v[2:3], off offset:16
	v_mov_b32_e32 v3, s8
	s_mov_b64 s[72:73], s[76:77]
	global_load_dword v8, v3, s[72:73]
	s_mov_b32 s8, 0xbfb8aa3b
	s_mov_b32 s17, 0xb2a5705f
	global_load_dword v3, v3, s[70:71]
	v_readlane_b32 s12, v252, 34
	v_readlane_b32 s13, v252, 35
	v_readlane_b32 s80, v251, 36
	v_readlane_b32 s81, v251, 37
	v_readlane_b32 s82, v251, 38
	v_readlane_b32 s83, v251, 39
	s_mov_b64 s[74:75], s[78:79]
	s_waitcnt vmcnt(3)
	v_mul_f32_e32 v0, 0xbfb8aa3b, v0
	v_exp_f32_e32 v0, v0
	s_waitcnt vmcnt(1)
	v_add_f32_e32 v2, v2, v8
	v_mul_f32_e64 v8, |v2|, s8
	v_fma_f32 v9, |v2|, s8, -v8
	v_rndne_f32_e32 v11, v8
	v_fma_f32 v9, |v2|, s17, v9
	v_sub_f32_e32 v8, v8, v11
	v_add_f32_e32 v8, v8, v9
	v_exp_f32_e32 v8, v8
	v_cvt_i32_f32_e32 v9, v11
	s_mov_b32 s17, 0x42ce8ed0
	v_cmp_ngt_f32_e64 vcc, |v2|, s17
	s_mov_b32 s17, 0xc2b17218
	v_ldexp_f32 v8, v8, v9
	v_cndmask_b32_e32 v8, 0, v8, vcc
	v_cmp_nlt_f32_e64 vcc, |v2|, s17
	v_max_f32_e32 v10, 0, v2
	s_mov_b32 s17, 0x3f2aaaab
	v_cndmask_b32_e32 v2, v207, v8, vcc
	v_add_f32_e32 v11, 1.0, v2
	v_add_f32_e32 v8, -1.0, v11
	v_sub_f32_e32 v9, v8, v11
	v_add_f32_e32 v9, 1.0, v9
	v_sub_f32_e32 v8, v2, v8
	v_add_f32_e32 v12, v8, v9
	v_frexp_mant_f32_e32 v8, v11
	v_cmp_gt_f32_e32 vcc, s17, v8
	v_cvt_f64_f32_e32 v[8:9], v11
	v_frexp_exp_i32_f64_e32 v8, v[8:9]
	v_subbrev_co_u32_e32 v8, vcc, 0, v8, vcc
	v_sub_u32_e32 v9, 0, v8
	v_ldexp_f32 v11, v11, v9
	v_ldexp_f32 v9, v12, v9
	v_add_f32_e32 v12, -1.0, v11
	v_add_f32_e32 v13, 1.0, v12
	v_sub_f32_e32 v13, v11, v13
	v_add_f32_e32 v13, v9, v13
	v_add_f32_e32 v14, v12, v13
	v_sub_f32_e32 v12, v12, v14
	v_add_f32_e32 v12, v13, v12
	v_add_f32_e32 v13, 1.0, v11
	v_add_f32_e32 v15, -1.0, v13
	v_sub_f32_e32 v11, v11, v15
	v_add_f32_e32 v9, v9, v11
	v_add_f32_e32 v11, v13, v9
	v_sub_f32_e32 v13, v13, v11
	v_add_f32_e32 v9, v9, v13
	v_rcp_f32_e32 v13, v11
	v_cvt_f32_i32_e32 v8, v8
	s_mov_b32 s17, 0x3f317218
	v_cmp_neq_f32_e32 vcc, s37, v2
	v_mul_f32_e32 v15, v14, v13
	v_mul_f32_e32 v16, v11, v15
	v_fma_f32 v17, v15, v11, -v16
	v_fmac_f32_e32 v17, v15, v9
	v_add_f32_e32 v18, v16, v17
	v_sub_f32_e32 v19, v14, v18
	v_sub_f32_e32 v14, v14, v19
	v_sub_f32_e32 v16, v18, v16
	v_sub_f32_e32 v14, v14, v18
	v_add_f32_e32 v12, v12, v14
	v_sub_f32_e32 v14, v16, v17
	v_add_f32_e32 v12, v14, v12
	v_add_f32_e32 v14, v19, v12
	v_mul_f32_e32 v16, v13, v14
	v_mul_f32_e32 v17, v11, v16
	v_fma_f32 v11, v16, v11, -v17
	v_fmac_f32_e32 v11, v16, v9
	v_sub_f32_e32 v9, v19, v14
	v_add_f32_e32 v9, v12, v9
	v_add_f32_e32 v12, v17, v11
	v_sub_f32_e32 v18, v14, v12
	v_sub_f32_e32 v14, v14, v18
	v_sub_f32_e32 v17, v12, v17
	v_sub_f32_e32 v12, v14, v12
	v_add_f32_e32 v9, v9, v12
	v_sub_f32_e32 v11, v17, v11
	v_add_f32_e32 v9, v11, v9
	v_add_f32_e32 v11, v15, v16
	v_add_f32_e32 v9, v18, v9
	v_sub_f32_e32 v12, v11, v15
	v_mul_f32_e32 v9, v13, v9
	v_sub_f32_e32 v12, v16, v12
	v_add_f32_e32 v9, v12, v9
	v_mul_f32_e32 v15, 0x3f317218, v8
	v_add_f32_e32 v12, v11, v9
	v_fma_f32 v16, v8, s17, -v15
	v_mul_f32_e32 v13, v12, v12
	v_fmac_f32_e32 v16, 0xb102e308, v8
	v_sub_f32_e32 v8, v12, v11
	v_fmamk_f32 v14, v13, 0x3e9b6dac, v197
	v_sub_f32_e32 v8, v9, v8
	v_add_f32_e32 v9, v15, v16
	v_fmaak_f32 v14, v13, v14, 0x3f2aaada
	v_sub_f32_e32 v11, v9, v15
	v_ldexp_f32 v15, v12, 1
	v_mul_f32_e32 v12, v12, v13
	v_mul_f32_e32 v12, v12, v14
	v_add_f32_e32 v13, v15, v12
	v_sub_f32_e32 v14, v13, v15
	v_ldexp_f32 v8, v8, 1
	v_sub_f32_e32 v12, v12, v14
	v_add_f32_e32 v8, v8, v12
	v_add_f32_e32 v12, v13, v8
	v_sub_f32_e32 v13, v12, v13
	v_sub_f32_e32 v8, v8, v13
	v_add_f32_e32 v13, v9, v12
	v_sub_f32_e32 v14, v13, v9
	v_sub_f32_e32 v15, v13, v14
	v_sub_f32_e32 v11, v16, v11
	v_sub_f32_e32 v9, v9, v15
	v_sub_f32_e32 v12, v12, v14
	v_add_f32_e32 v9, v12, v9
	v_add_f32_e32 v12, v11, v8
	v_sub_f32_e32 v14, v12, v11
	v_sub_f32_e32 v15, v12, v14
	v_sub_f32_e32 v11, v11, v15
	v_sub_f32_e32 v8, v8, v14
	v_add_f32_e32 v9, v12, v9
	v_add_f32_e32 v8, v8, v11
	v_add_f32_e32 v11, v13, v9
	v_sub_f32_e32 v12, v11, v13
	v_sub_f32_e32 v9, v9, v12
	v_add_f32_e32 v8, v8, v9
	v_add_f32_e32 v8, v11, v8
	s_mov_b32 s17, 0x33800000
	v_cndmask_b32_e32 v8, v207, v8, vcc
	v_cmp_lt_f32_e64 vcc, |v2|, s17
	v_add_f32_e32 v0, 1.0, v0
	s_nop 0
	v_cndmask_b32_e32 v2, v8, v2, vcc
	s_waitcnt vmcnt(0)
	v_mul_f32_e32 v8, 0x3fb8aa3b, v3
	v_add_f32_e32 v2, v10, v2
	v_fma_f32 v9, v3, s86, -v8
	v_rndne_f32_e32 v10, v8
	v_fmac_f32_e32 v9, 0x32a5705f, v3
	v_sub_f32_e32 v8, v8, v10
	v_add_f32_e32 v8, v8, v9
	v_exp_f32_e32 v8, v8
	v_cvt_i32_f32_e32 v9, v10
	v_cmp_ngt_f32_e32 vcc, s87, v3
	v_add_u32_e32 v10, -1, v154
	v_ldexp_f32 v8, v8, v9
	v_cndmask_b32_e32 v8, 0, v8, vcc
	v_cmp_nlt_f32_e32 vcc, s88, v3
	v_and_b32_e32 v3, 64, v154
	s_nop 0
	v_cndmask_b32_e32 v8, v207, v8, vcc
	v_cmp_lt_i32_e32 vcc, v10, v3
	v_mul_f32_e64 v9, v2, -v8
	s_nop 0
	v_cndmask_b32_e32 v10, v10, v154, vcc
	v_lshlrev_b32_e32 v10, 2, v10
	ds_bpermute_b32 v10, v10, v9
	s_waitcnt lgkmcnt(0)
	v_fma_f32 v2, v2, -v8, v10
	v_add_u32_e32 v8, -2, v154
	v_cmp_lt_i32_e32 vcc, v8, v3
	v_cndmask_b32_e64 v2, v2, v9, s[66:67]
	s_nop 0
	v_cndmask_b32_e32 v8, v8, v154, vcc
	v_lshlrev_b32_e32 v8, 2, v8
	ds_bpermute_b32 v8, v8, v2
	s_waitcnt lgkmcnt(0)
	v_add_f32_e32 v8, v2, v8
	v_cndmask_b32_e64 v2, v8, v2, s[12:13]
	v_add_u32_e32 v8, -4, v154
	v_cmp_lt_i32_e32 vcc, v8, v3
	v_readlane_b32 s12, v252, 36
	v_readlane_b32 s13, v252, 37
	v_cndmask_b32_e32 v8, v8, v154, vcc
	v_lshlrev_b32_e32 v8, 2, v8
	ds_bpermute_b32 v8, v8, v2
	s_waitcnt lgkmcnt(0)
	v_add_f32_e32 v8, v2, v8
	v_cndmask_b32_e64 v2, v8, v2, s[12:13]
	v_add_u32_e32 v8, -8, v154
	v_cmp_lt_i32_e32 vcc, v8, v3
	v_readlane_b32 s12, v252, 38
	v_readlane_b32 s13, v252, 39
	v_cndmask_b32_e32 v8, v8, v154, vcc
	v_lshlrev_b32_e32 v8, 2, v8
	ds_bpermute_b32 v8, v8, v2
	s_waitcnt lgkmcnt(0)
	v_add_f32_e32 v8, v2, v8
	v_cndmask_b32_e64 v2, v8, v2, s[12:13]
	v_add_u32_e32 v8, -16, v154
	v_cmp_lt_i32_e32 vcc, v8, v3
	v_readlane_b32 s12, v252, 40
	v_readlane_b32 s13, v252, 41
	v_cndmask_b32_e32 v8, v8, v154, vcc
	v_lshlrev_b32_e32 v8, 2, v8
	ds_bpermute_b32 v8, v8, v2
	s_waitcnt lgkmcnt(0)
	v_add_f32_e32 v8, v2, v8
	v_cndmask_b32_e64 v2, v8, v2, s[12:13]
	v_subrev_u32_e32 v8, 32, v154
	v_cmp_lt_i32_e32 vcc, v8, v3
	s_nop 1
	v_cndmask_b32_e32 v3, v8, v154, vcc
	v_lshlrev_b32_e32 v3, 2, v3
	ds_bpermute_b32 v3, v3, v2
	s_waitcnt lgkmcnt(0)
	v_add_f32_e32 v3, v2, v3
	v_cndmask_b32_e64 v2, v3, v2, s[4:5]
	v_div_scale_f32 v3, s[92:93], v0, v0, 1.0
	v_rcp_f32_e32 v8, v3
	s_nop 0
	v_fma_f32 v9, -v3, v8, 1.0
	v_fmac_f32_e32 v8, v9, v8
	v_div_scale_f32 v9, vcc, 1.0, v0, 1.0
	v_mul_f32_e32 v10, v9, v8
	v_fma_f32 v11, -v3, v10, v9
	v_fmac_f32_e32 v10, v11, v8
	v_fma_f32 v3, -v3, v10, v9
	v_div_fmas_f32 v3, v3, v8, v10
	v_div_fixup_f32 v0, v3, v0, 1.0
	ds_write2st64_b32 v140, v2, v0 offset0:192 offset1:193
	v_mul_f32_e32 v0, 0x3fb8aa3b, v2
	v_fma_f32 v3, v2, s86, -v0
	v_rndne_f32_e32 v8, v0
	v_fmac_f32_e32 v3, 0x32a5705f, v2
	v_sub_f32_e32 v0, v0, v8
	v_add_f32_e32 v0, v0, v3
	v_exp_f32_e32 v0, v0
	v_cvt_i32_f32_e32 v3, v8
	v_cmp_ngt_f32_e32 vcc, s87, v2
	v_ldexp_f32 v0, v0, v3
	s_nop 0
	v_cndmask_b32_e32 v0, 0, v0, vcc
	v_cmp_nlt_f32_e32 vcc, s88, v2
	s_nop 1
	v_cndmask_b32_e32 v0, v207, v0, vcc
	ds_write_b32 v140, v0 offset:49664
.LBB0_215:
	s_or_b64 exec, exec, s[0:1]
	s_waitcnt vmcnt(12)
	ds_write_b128 v22, v[56:59]
	ds_write_b128 v23, v[60:63]
	s_lshl_b32 s16, s16, 7
	s_cmp_lg_u32 s15, 31
	s_waitcnt lgkmcnt(0)
	s_barrier
	s_cbranch_scc1 .LBB0_219
	v_readlane_b32 s68, v251, 56
	s_or_b32 s15, s19, 0x7fd
	s_mul_i32 s14, s14, 3
	s_mov_b64 s[0:1], 0
	v_mov_b32_e32 v0, v162
	v_readlane_b32 s69, v251, 57
	v_readlane_b32 s70, v251, 58
	v_readlane_b32 s71, v251, 59
	v_readlane_b32 s72, v251, 60
	v_readlane_b32 s73, v251, 61
	v_readlane_b32 s74, v251, 62
	v_readlane_b32 s75, v251, 63
	v_readlane_b32 s76, v252, 0
	v_readlane_b32 s77, v252, 1
	v_readlane_b32 s78, v252, 2
	v_readlane_b32 s79, v252, 3
	v_readlane_b32 s80, v252, 4
	v_readlane_b32 s81, v252, 5
	v_readlane_b32 s82, v252, 6
	v_readlane_b32 s83, v252, 7

.LBB0_219:
	s_and_b32 s15, s64, 31
	s_bfe_u32 s14, s64, 0x20005
	s_lshr_b32 s0, s64, 7
	s_mul_i32 s8, s0, 0xa00000
	s_lshl_b32 s1, s14, 8
	s_add_u32 s8, s8, s1
	s_add_u32 s8, s8, 0x400
	s_add_u32 s16, s28, s8
	s_addc_u32 s17, s29, 0
	s_mov_b32 s18, 0xbfb8aa3b
	s_mov_b32 s19, 0
	s_mul_i32 s0, s64, 0x12000
	s_mul_hi_u32 s1, s64, 0x12000
	s_add_u32 s92, s30, s0
	s_addc_u32 s93, s31, s1
	v_lshrrev_b32_e32 v119, 2, v162
	v_and_b32_e32 v121, 3, v162
	v_mul_u32_u24_e32 v255, 0x90, v121
	v_add_u32_e32 v255, 0xc400, v255
	v_lshlrev_b32_e32 v0, 2, v119
	ds_read_b32 v230, v0 offset:49664
	ds_read_b32 v216, v0 offset:49152
	ds_read_b32 v217, v1 offset:49404
	ds_read_b128 v[48:51], v255 offset:0
	ds_read_b128 v[56:59], v255 offset:16
	ds_read_b128 v[60:63], v255 offset:1728
	ds_read_b128 v[220:223], v255 offset:1744
	v_lshlrev_b32_e32 v111, 8, v119
	v_and_b32_e32 v0, 15, v119
	v_lshlrev_b32_e32 v113, 2, v121
	v_xor_b32_e32 v113, v113, v0
	v_lshlrev_b32_e32 v115, 12, v121
	v_lshl_add_u32 v115, v119, 1, v115
	v_add_u32_e32 v115, 0xc000, v115
	v_lshl_add_u32 v117, v121, 6, v111
	v_add_u32_e32 v117, 0x8000, v117
	s_lshl_b32 s0, s15, 6
	s_sub_u32 s0, s0, 3
	v_add_u32_e32 v121, s0, v119
	v_cmp_lt_i32_e64 s[70:71], -1, v121
	v_add_u32_e32 v121, 1, v121
	v_cmp_lt_i32_e64 s[72:73], -1, v121
	v_add_u32_e32 v121, 1, v121
	v_cmp_lt_i32_e64 s[74:75], -1, v121
	s_waitcnt lgkmcnt(4)
	v_sub_f32_e32 v119, v217, v216
	v_mul_f32_e32 v121, 0x3fb8aa3b, v119
	v_fma_f32 v0, v119, s86, -v121
	v_rndne_f32_e32 v216, v121
	v_fmac_f32_e32 v0, 0x32a5705f, v119
	v_sub_f32_e32 v121, v121, v216
	v_add_f32_e32 v121, v121, v0
	v_exp_f32_e32 v121, v121
	v_cvt_i32_f32_e32 v0, v216
	v_cmp_ngt_f32_e32 vcc, s87, v119
	v_ldexp_f32 v121, v121, v0
	s_nop 0
	v_cndmask_b32_e32 v121, 0, v121, vcc
	v_cmp_nlt_f32_e32 vcc, s88, v119
	v_mov_b32_e32 v0, 0x7f800000
	s_nop 1
	v_cndmask_b32_e32 v231, v0, v121, vcc
	v_mov_b32_e32 v218, 0
	s_cmp_lg_u32 s15, 0
	s_cbranch_scc1 .Lpb_sk_0
	s_waitcnt vmcnt(9)
	v_cndmask_b32_e64 v28, 0, v28, s[70:71]
	v_cndmask_b32_e64 v29, 0, v29, s[70:71]
	v_cndmask_b32_e64 v30, 0, v30, s[70:71]
	v_cndmask_b32_e64 v31, 0, v31, s[70:71]
	v_cndmask_b32_e64 v32, 0, v32, s[72:73]
	v_cndmask_b32_e64 v33, 0, v33, s[72:73]
	v_cndmask_b32_e64 v34, 0, v34, s[72:73]
	v_cndmask_b32_e64 v35, 0, v35, s[72:73]
	v_cndmask_b32_e64 v36, 0, v36, s[74:75]
	v_cndmask_b32_e64 v37, 0, v37, s[74:75]
	v_cndmask_b32_e64 v38, 0, v38, s[74:75]
	v_cndmask_b32_e64 v39, 0, v39, s[74:75]
.Lpb_sk_0:
	s_waitcnt vmcnt(11)
	v_lshlrev_b32_e32 v224, 16, v28
	v_and_b32_e32 v225, 0xffff0000, v28
	v_lshlrev_b32_e32 v226, 16, v29
	v_and_b32_e32 v227, 0xffff0000, v29
	s_waitcnt lgkmcnt(3)
	v_pk_fma_f32 v[126:127], v[48:49], v[224:225], 0 op_sel_hi:[1,1,0]
	v_pk_fma_f32 v[128:129], v[50:51], v[226:227], 0 op_sel_hi:[1,1,0]
	ds_read_b128 v[48:51], v255 offset:3456
	v_lshlrev_b32_e32 v224, 16, v30
	v_and_b32_e32 v225, 0xffff0000, v30
	v_lshlrev_b32_e32 v226, 16, v31
	v_and_b32_e32 v227, 0xffff0000, v31
	s_waitcnt lgkmcnt(3)
	v_pk_fma_f32 v[130:131], v[56:57], v[224:225], 0 op_sel_hi:[1,1,0]
	v_pk_fma_f32 v[132:133], v[58:59], v[226:227], 0 op_sel_hi:[1,1,0]
	ds_read_b128 v[56:59], v255 offset:3472
	global_load_dwordx4 v[28:31], v248, s[16:17] offset:48
	s_waitcnt vmcnt(11)
	v_lshlrev_b32_e32 v224, 16, v32
	v_and_b32_e32 v225, 0xffff0000, v32
	v_lshlrev_b32_e32 v226, 16, v33
	v_and_b32_e32 v227, 0xffff0000, v33
	s_waitcnt lgkmcnt(3)
	v_pk_fma_f32 v[126:127], v[60:61], v[224:225], v[126:127]
	v_pk_fma_f32 v[128:129], v[62:63], v[226:227], v[128:129]
	ds_read_b128 v[60:63], v255 offset:5184
	v_lshlrev_b32_e32 v224, 16, v34
	v_and_b32_e32 v225, 0xffff0000, v34
	v_lshlrev_b32_e32 v226, 16, v35
	v_and_b32_e32 v227, 0xffff0000, v35
	s_waitcnt lgkmcnt(3)
	v_pk_fma_f32 v[130:131], v[220:221], v[224:225], v[130:131]
	v_pk_fma_f32 v[132:133], v[222:223], v[226:227], v[132:133]
	ds_read_b128 v[220:223], v255 offset:5200
	global_load_dwordx4 v[32:35], v249, s[16:17] offset:48
	s_waitcnt vmcnt(11)
	v_lshlrev_b32_e32 v224, 16, v36
	v_and_b32_e32 v225, 0xffff0000, v36
	v_lshlrev_b32_e32 v226, 16, v37
	v_and_b32_e32 v227, 0xffff0000, v37
	s_waitcnt lgkmcnt(3)
	v_pk_fma_f32 v[126:127], v[48:49], v[224:225], v[126:127]
	v_pk_fma_f32 v[128:129], v[50:51], v[226:227], v[128:129]
	ds_read_b128 v[48:51], v255 offset:32
	v_lshlrev_b32_e32 v224, 16, v38
	v_and_b32_e32 v225, 0xffff0000, v38
	v_lshlrev_b32_e32 v226, 16, v39
	v_and_b32_e32 v227, 0xffff0000, v39
	s_waitcnt lgkmcnt(3)
	v_pk_fma_f32 v[130:131], v[56:57], v[224:225], v[130:131]
	v_pk_fma_f32 v[132:133], v[58:59], v[226:227], v[132:133]
	ds_read_b128 v[56:59], v255 offset:48
	global_load_dwordx4 v[36:39], v253, s[16:17] offset:48
	s_waitcnt vmcnt(11)
	v_lshlrev_b32_e32 v224, 16, v40
	v_and_b32_e32 v225, 0xffff0000, v40
	v_lshlrev_b32_e32 v226, 16, v41
	v_and_b32_e32 v227, 0xffff0000, v41
	s_waitcnt lgkmcnt(3)
	v_pk_fma_f32 v[126:127], v[60:61], v[224:225], v[126:127]
	v_pk_fma_f32 v[128:129], v[62:63], v[226:227], v[128:129]
	ds_read_b128 v[60:63], v255 offset:1760
	v_lshlrev_b32_e32 v224, 16, v42
	v_and_b32_e32 v225, 0xffff0000, v42
	v_lshlrev_b32_e32 v226, 16, v43
	v_and_b32_e32 v227, 0xffff0000, v43
	s_waitcnt lgkmcnt(3)
	v_pk_fma_f32 v[130:131], v[220:221], v[224:225], v[130:131]
	v_pk_fma_f32 v[132:133], v[222:223], v[226:227], v[132:133]
	ds_read_b128 v[220:223], v255 offset:1776
	global_load_dwordx4 v[40:43], v254, s[16:17] offset:48
	v_pk_mul_f32 v[224:225], v[126:127], s[18:19] op_sel_hi:[1,0]
	v_pk_mul_f32 v[226:227], v[128:129], s[18:19] op_sel_hi:[1,0]
	v_pk_mul_f32 v[2:3], v[130:131], s[18:19] op_sel_hi:[1,0]
	v_pk_mul_f32 v[134:135], v[132:133], s[18:19] op_sel_hi:[1,0]
	v_exp_f32_e32 v224, v224
	v_exp_f32_e32 v225, v225
	v_exp_f32_e32 v226, v226
	v_exp_f32_e32 v227, v227
	v_exp_f32_e32 v2, v2
	v_exp_f32_e32 v3, v3
	v_exp_f32_e32 v134, v134
	v_exp_f32_e32 v135, v135
	v_pk_add_f32 v[224:225], v[224:225], 1.0 op_sel_hi:[1,0]
	v_pk_add_f32 v[226:227], v[226:227], 1.0 op_sel_hi:[1,0]
	v_pk_add_f32 v[2:3], v[2:3], 1.0 op_sel_hi:[1,0]
	v_pk_add_f32 v[134:135], v[134:135], 1.0 op_sel_hi:[1,0]
	v_rcp_f32_e32 v224, v224
	v_rcp_f32_e32 v225, v225
	v_rcp_f32_e32 v226, v226
	v_rcp_f32_e32 v227, v227
	v_rcp_f32_e32 v2, v2
	v_rcp_f32_e32 v3, v3
	v_rcp_f32_e32 v134, v134
	v_rcp_f32_e32 v135, v135
	v_pk_mul_f32 v[8:9], v[126:127], v[224:225]
	v_pk_mul_f32 v[10:11], v[128:129], v[226:227]
	v_pk_mul_f32 v[12:13], v[130:131], v[2:3]
	v_pk_mul_f32 v[14:15], v[132:133], v[134:135]
	v_pk_mul_f32 v[216:217], v[8:9], v[8:9]
	v_add_f32_e32 v218, v218, v216
	v_add_f32_e32 v218, v217, v218
	v_pk_mul_f32 v[216:217], v[10:11], v[10:11]
	v_add_f32_e32 v218, v218, v216
	v_add_f32_e32 v218, v217, v218
	v_pk_mul_f32 v[216:217], v[12:13], v[12:13]
	v_add_f32_e32 v218, v218, v216
	v_add_f32_e32 v218, v217, v218
	v_pk_mul_f32 v[216:217], v[14:15], v[14:15]
	v_add_f32_e32 v218, v218, v216
	v_add_f32_e32 v218, v217, v218
	s_cmp_lg_u32 s15, 0
	s_cbranch_scc1 .Lpb_sk_1
	s_waitcnt vmcnt(9)
	v_cndmask_b32_e64 v44, 0, v44, s[70:71]
	v_cndmask_b32_e64 v45, 0, v45, s[70:71]
	v_cndmask_b32_e64 v46, 0, v46, s[70:71]
	v_cndmask_b32_e64 v47, 0, v47, s[70:71]
	v_cndmask_b32_e64 v52, 0, v52, s[72:73]
	v_cndmask_b32_e64 v53, 0, v53, s[72:73]
	v_cndmask_b32_e64 v54, 0, v54, s[72:73]
	v_cndmask_b32_e64 v55, 0, v55, s[72:73]
	v_cndmask_b32_e64 v168, 0, v168, s[74:75]
	v_cndmask_b32_e64 v169, 0, v169, s[74:75]
	v_cndmask_b32_e64 v170, 0, v170, s[74:75]
	v_cndmask_b32_e64 v171, 0, v171, s[74:75]
.Lpb_sk_1:
	s_waitcnt vmcnt(11)
	v_lshlrev_b32_e32 v224, 16, v44
	v_and_b32_e32 v225, 0xffff0000, v44
	v_lshlrev_b32_e32 v226, 16, v45
	v_and_b32_e32 v227, 0xffff0000, v45
	s_waitcnt lgkmcnt(3)
	v_pk_fma_f32 v[126:127], v[48:49], v[224:225], 0 op_sel_hi:[1,1,0]
	v_pk_fma_f32 v[128:129], v[50:51], v[226:227], 0 op_sel_hi:[1,1,0]
	ds_read_b128 v[48:51], v255 offset:3488
	v_lshlrev_b32_e32 v224, 16, v46
	v_and_b32_e32 v225, 0xffff0000, v46
	v_lshlrev_b32_e32 v226, 16, v47
	v_and_b32_e32 v227, 0xffff0000, v47
	s_waitcnt lgkmcnt(3)
	v_pk_fma_f32 v[130:131], v[56:57], v[224:225], 0 op_sel_hi:[1,1,0]
	v_pk_fma_f32 v[132:133], v[58:59], v[226:227], 0 op_sel_hi:[1,1,0]
	ds_read_b128 v[56:59], v255 offset:3504
	global_load_dwordx4 v[44:47], v248, s[16:17] offset:1024
	s_waitcnt vmcnt(11)
	v_lshlrev_b32_e32 v224, 16, v52
	v_and_b32_e32 v225, 0xffff0000, v52
	v_lshlrev_b32_e32 v226, 16, v53
	v_and_b32_e32 v227, 0xffff0000, v53
	s_waitcnt lgkmcnt(3)
	v_pk_fma_f32 v[126:127], v[60:61], v[224:225], v[126:127]
	v_pk_fma_f32 v[128:129], v[62:63], v[226:227], v[128:129]
	ds_read_b128 v[60:63], v255 offset:5216
	v_lshlrev_b32_e32 v224, 16, v54
	v_and_b32_e32 v225, 0xffff0000, v54
	v_lshlrev_b32_e32 v226, 16, v55
	v_and_b32_e32 v227, 0xffff0000, v55
	s_waitcnt lgkmcnt(3)
	v_pk_fma_f32 v[130:131], v[220:221], v[224:225], v[130:131]
	v_pk_fma_f32 v[132:133], v[222:223], v[226:227], v[132:133]
	ds_read_b128 v[220:223], v255 offset:5232
	global_load_dwordx4 v[52:55], v249, s[16:17] offset:1024
	s_waitcnt vmcnt(11)
	v_lshlrev_b32_e32 v224, 16, v168
	v_and_b32_e32 v225, 0xffff0000, v168
	v_lshlrev_b32_e32 v226, 16, v169
	v_and_b32_e32 v227, 0xffff0000, v169
	s_waitcnt lgkmcnt(3)
	v_pk_fma_f32 v[126:127], v[48:49], v[224:225], v[126:127]
	v_pk_fma_f32 v[128:129], v[50:51], v[226:227], v[128:129]
	ds_read_b128 v[48:51], v255 offset:64
	v_lshlrev_b32_e32 v224, 16, v170
	v_and_b32_e32 v225, 0xffff0000, v170
	v_lshlrev_b32_e32 v226, 16, v171
	v_and_b32_e32 v227, 0xffff0000, v171
	s_waitcnt lgkmcnt(3)
	v_pk_fma_f32 v[130:131], v[56:57], v[224:225], v[130:131]
	v_pk_fma_f32 v[132:133], v[58:59], v[226:227], v[132:133]
	ds_read_b128 v[56:59], v255 offset:80
	global_load_dwordx4 v[168:171], v253, s[16:17] offset:1024
	s_waitcnt vmcnt(11)
	v_lshlrev_b32_e32 v224, 16, v172
	v_and_b32_e32 v225, 0xffff0000, v172
	v_lshlrev_b32_e32 v226, 16, v173
	v_and_b32_e32 v227, 0xffff0000, v173
	s_waitcnt lgkmcnt(3)
	v_pk_fma_f32 v[126:127], v[60:61], v[224:225], v[126:127]
	v_pk_fma_f32 v[128:129], v[62:63], v[226:227], v[128:129]
	ds_read_b128 v[60:63], v255 offset:1792
	v_lshlrev_b32_e32 v224, 16, v174
	v_and_b32_e32 v225, 0xffff0000, v174
	v_lshlrev_b32_e32 v226, 16, v175
	v_and_b32_e32 v227, 0xffff0000, v175
	s_waitcnt lgkmcnt(3)
	v_pk_fma_f32 v[130:131], v[220:221], v[224:225], v[130:131]
	v_pk_fma_f32 v[132:133], v[222:223], v[226:227], v[132:133]
	ds_read_b128 v[220:223], v255 offset:1808
	global_load_dwordx4 v[172:175], v254, s[16:17] offset:1024
	v_pk_mul_f32 v[224:225], v[126:127], s[18:19] op_sel_hi:[1,0]
	v_pk_mul_f32 v[226:227], v[128:129], s[18:19] op_sel_hi:[1,0]
	v_pk_mul_f32 v[2:3], v[130:131], s[18:19] op_sel_hi:[1,0]
	v_pk_mul_f32 v[134:135], v[132:133], s[18:19] op_sel_hi:[1,0]
	v_exp_f32_e32 v224, v224
	v_exp_f32_e32 v225, v225
	v_exp_f32_e32 v226, v226
	v_exp_f32_e32 v227, v227
	v_exp_f32_e32 v2, v2
	v_exp_f32_e32 v3, v3
	v_exp_f32_e32 v134, v134
	v_exp_f32_e32 v135, v135
	v_pk_add_f32 v[224:225], v[224:225], 1.0 op_sel_hi:[1,0]
	v_pk_add_f32 v[226:227], v[226:227], 1.0 op_sel_hi:[1,0]
	v_pk_add_f32 v[2:3], v[2:3], 1.0 op_sel_hi:[1,0]
	v_pk_add_f32 v[134:135], v[134:135], 1.0 op_sel_hi:[1,0]
	v_rcp_f32_e32 v224, v224
	v_rcp_f32_e32 v225, v225
	v_rcp_f32_e32 v226, v226
	v_rcp_f32_e32 v227, v227
	v_rcp_f32_e32 v2, v2
	v_rcp_f32_e32 v3, v3
	v_rcp_f32_e32 v134, v134
	v_rcp_f32_e32 v135, v135
	v_pk_mul_f32 v[16:17], v[126:127], v[224:225]
	v_pk_mul_f32 v[18:19], v[128:129], v[226:227]
	v_pk_mul_f32 v[20:21], v[130:131], v[2:3]
	v_pk_mul_f32 v[22:23], v[132:133], v[134:135]
	v_pk_mul_f32 v[216:217], v[16:17], v[16:17]
	v_add_f32_e32 v218, v218, v216
	v_add_f32_e32 v218, v217, v218
	v_pk_mul_f32 v[216:217], v[18:19], v[18:19]
	v_add_f32_e32 v218, v218, v216
	v_add_f32_e32 v218, v217, v218
	v_pk_mul_f32 v[216:217], v[20:21], v[20:21]
	v_add_f32_e32 v218, v218, v216
	v_add_f32_e32 v218, v217, v218
	v_pk_mul_f32 v[216:217], v[22:23], v[22:23]
	v_add_f32_e32 v218, v218, v216
	v_add_f32_e32 v218, v217, v218
	s_cmp_lg_u32 s15, 0
	s_cbranch_scc1 .Lpb_sk_2
	s_waitcnt vmcnt(9)
	v_cndmask_b32_e64 v176, 0, v176, s[70:71]
	v_cndmask_b32_e64 v177, 0, v177, s[70:71]
	v_cndmask_b32_e64 v178, 0, v178, s[70:71]
	v_cndmask_b32_e64 v179, 0, v179, s[70:71]
	v_cndmask_b32_e64 v180, 0, v180, s[72:73]
	v_cndmask_b32_e64 v181, 0, v181, s[72:73]
	v_cndmask_b32_e64 v182, 0, v182, s[72:73]
	v_cndmask_b32_e64 v183, 0, v183, s[72:73]
	v_cndmask_b32_e64 v198, 0, v198, s[74:75]
	v_cndmask_b32_e64 v199, 0, v199, s[74:75]
	v_cndmask_b32_e64 v200, 0, v200, s[74:75]
	v_cndmask_b32_e64 v201, 0, v201, s[74:75]
.Lpb_sk_2:
	s_waitcnt vmcnt(11)
	v_lshlrev_b32_e32 v224, 16, v176
	v_and_b32_e32 v225, 0xffff0000, v176
	v_lshlrev_b32_e32 v226, 16, v177
	v_and_b32_e32 v227, 0xffff0000, v177
	s_waitcnt lgkmcnt(3)
	v_pk_fma_f32 v[126:127], v[48:49], v[224:225], 0 op_sel_hi:[1,1,0]
	v_pk_fma_f32 v[128:129], v[50:51], v[226:227], 0 op_sel_hi:[1,1,0]
	ds_read_b128 v[48:51], v255 offset:3520
	v_lshlrev_b32_e32 v224, 16, v178
	v_and_b32_e32 v225, 0xffff0000, v178
	v_lshlrev_b32_e32 v226, 16, v179
	v_and_b32_e32 v227, 0xffff0000, v179
	s_waitcnt lgkmcnt(3)
	v_pk_fma_f32 v[130:131], v[56:57], v[224:225], 0 op_sel_hi:[1,1,0]
	v_pk_fma_f32 v[132:133], v[58:59], v[226:227], 0 op_sel_hi:[1,1,0]
	ds_read_b128 v[56:59], v255 offset:3536
	global_load_dwordx4 v[176:179], v248, s[16:17] offset:1040
	s_waitcnt vmcnt(11)
	v_lshlrev_b32_e32 v224, 16, v180
	v_and_b32_e32 v225, 0xffff0000, v180
	v_lshlrev_b32_e32 v226, 16, v181
	v_and_b32_e32 v227, 0xffff0000, v181
	s_waitcnt lgkmcnt(3)
	v_pk_fma_f32 v[126:127], v[60:61], v[224:225], v[126:127]
	v_pk_fma_f32 v[128:129], v[62:63], v[226:227], v[128:129]
	ds_read_b128 v[60:63], v255 offset:5248
	v_lshlrev_b32_e32 v224, 16, v182
	v_and_b32_e32 v225, 0xffff0000, v182
	v_lshlrev_b32_e32 v226, 16, v183
	v_and_b32_e32 v227, 0xffff0000, v183
	s_waitcnt lgkmcnt(3)
	v_pk_fma_f32 v[130:131], v[220:221], v[224:225], v[130:131]
	v_pk_fma_f32 v[132:133], v[222:223], v[226:227], v[132:133]
	ds_read_b128 v[220:223], v255 offset:5264
	global_load_dwordx4 v[180:183], v249, s[16:17] offset:1040
	s_waitcnt vmcnt(11)
	v_lshlrev_b32_e32 v224, 16, v198
	v_and_b32_e32 v225, 0xffff0000, v198
	v_lshlrev_b32_e32 v226, 16, v199
	v_and_b32_e32 v227, 0xffff0000, v199
	s_waitcnt lgkmcnt(3)
	v_pk_fma_f32 v[126:127], v[48:49], v[224:225], v[126:127]
	v_pk_fma_f32 v[128:129], v[50:51], v[226:227], v[128:129]
	ds_read_b128 v[48:51], v255 offset:96
	v_lshlrev_b32_e32 v224, 16, v200
	v_and_b32_e32 v225, 0xffff0000, v200
	v_lshlrev_b32_e32 v226, 16, v201
	v_and_b32_e32 v227, 0xffff0000, v201
	s_waitcnt lgkmcnt(3)
	v_pk_fma_f32 v[130:131], v[56:57], v[224:225], v[130:131]
	v_pk_fma_f32 v[132:133], v[58:59], v[226:227], v[132:133]
	ds_read_b128 v[56:59], v255 offset:112
	global_load_dwordx4 v[198:201], v253, s[16:17] offset:1040
	s_waitcnt vmcnt(11)
	v_lshlrev_b32_e32 v224, 16, v210
	v_and_b32_e32 v225, 0xffff0000, v210
	v_lshlrev_b32_e32 v226, 16, v211
	v_and_b32_e32 v227, 0xffff0000, v211
	s_waitcnt lgkmcnt(3)
	v_pk_fma_f32 v[126:127], v[60:61], v[224:225], v[126:127]
	v_pk_fma_f32 v[128:129], v[62:63], v[226:227], v[128:129]
	ds_read_b128 v[60:63], v255 offset:1824
	v_lshlrev_b32_e32 v224, 16, v212
	v_and_b32_e32 v225, 0xffff0000, v212
	v_lshlrev_b32_e32 v226, 16, v213
	v_and_b32_e32 v227, 0xffff0000, v213
	s_waitcnt lgkmcnt(3)
	v_pk_fma_f32 v[130:131], v[220:221], v[224:225], v[130:131]
	v_pk_fma_f32 v[132:133], v[222:223], v[226:227], v[132:133]
	ds_read_b128 v[220:223], v255 offset:1840
	global_load_dwordx4 v[210:213], v254, s[16:17] offset:1040
	v_pk_mul_f32 v[224:225], v[126:127], s[18:19] op_sel_hi:[1,0]
	v_pk_mul_f32 v[226:227], v[128:129], s[18:19] op_sel_hi:[1,0]
	v_pk_mul_f32 v[2:3], v[130:131], s[18:19] op_sel_hi:[1,0]
	v_pk_mul_f32 v[134:135], v[132:133], s[18:19] op_sel_hi:[1,0]
	v_exp_f32_e32 v224, v224
	v_exp_f32_e32 v225, v225
	v_exp_f32_e32 v226, v226
	v_exp_f32_e32 v227, v227
	v_exp_f32_e32 v2, v2
	v_exp_f32_e32 v3, v3
	v_exp_f32_e32 v134, v134
	v_exp_f32_e32 v135, v135
	v_pk_add_f32 v[224:225], v[224:225], 1.0 op_sel_hi:[1,0]
	v_pk_add_f32 v[226:227], v[226:227], 1.0 op_sel_hi:[1,0]
	v_pk_add_f32 v[2:3], v[2:3], 1.0 op_sel_hi:[1,0]
	v_pk_add_f32 v[134:135], v[134:135], 1.0 op_sel_hi:[1,0]
	v_rcp_f32_e32 v224, v224
	v_rcp_f32_e32 v225, v225
	v_rcp_f32_e32 v226, v226
	v_rcp_f32_e32 v227, v227
	v_rcp_f32_e32 v2, v2
	v_rcp_f32_e32 v3, v3
	v_rcp_f32_e32 v134, v134
	v_rcp_f32_e32 v135, v135
	v_pk_mul_f32 v[24:25], v[126:127], v[224:225]
	v_pk_mul_f32 v[26:27], v[128:129], v[226:227]
	v_pk_mul_f32 v[64:65], v[130:131], v[2:3]
	v_pk_mul_f32 v[66:67], v[132:133], v[134:135]
	v_pk_mul_f32 v[216:217], v[24:25], v[24:25]
	v_add_f32_e32 v218, v218, v216
	v_add_f32_e32 v218, v217, v218
	v_pk_mul_f32 v[216:217], v[26:27], v[26:27]
	v_add_f32_e32 v218, v218, v216
	v_add_f32_e32 v218, v217, v218
	v_pk_mul_f32 v[216:217], v[64:65], v[64:65]
	v_add_f32_e32 v218, v218, v216
	v_add_f32_e32 v218, v217, v218
	v_pk_mul_f32 v[216:217], v[66:67], v[66:67]
	v_add_f32_e32 v218, v218, v216
	v_add_f32_e32 v218, v217, v218
	s_cmp_lg_u32 s15, 0
	s_cbranch_scc1 .Lpb_sk_3
	s_waitcnt vmcnt(9)
	v_cndmask_b32_e64 v28, 0, v28, s[70:71]
	v_cndmask_b32_e64 v29, 0, v29, s[70:71]
	v_cndmask_b32_e64 v30, 0, v30, s[70:71]
	v_cndmask_b32_e64 v31, 0, v31, s[70:71]
	v_cndmask_b32_e64 v32, 0, v32, s[72:73]
	v_cndmask_b32_e64 v33, 0, v33, s[72:73]
	v_cndmask_b32_e64 v34, 0, v34, s[72:73]
	v_cndmask_b32_e64 v35, 0, v35, s[72:73]
	v_cndmask_b32_e64 v36, 0, v36, s[74:75]
	v_cndmask_b32_e64 v37, 0, v37, s[74:75]
	v_cndmask_b32_e64 v38, 0, v38, s[74:75]
	v_cndmask_b32_e64 v39, 0, v39, s[74:75]
.Lpb_sk_3:
	s_waitcnt vmcnt(11)
	v_lshlrev_b32_e32 v224, 16, v28
	v_and_b32_e32 v225, 0xffff0000, v28
	v_lshlrev_b32_e32 v226, 16, v29
	v_and_b32_e32 v227, 0xffff0000, v29
	s_waitcnt lgkmcnt(3)
	v_pk_fma_f32 v[126:127], v[48:49], v[224:225], 0 op_sel_hi:[1,1,0]
	v_pk_fma_f32 v[128:129], v[50:51], v[226:227], 0 op_sel_hi:[1,1,0]
	ds_read_b128 v[48:51], v255 offset:3552
	v_lshlrev_b32_e32 v224, 16, v30
	v_and_b32_e32 v225, 0xffff0000, v30
	v_lshlrev_b32_e32 v226, 16, v31
	v_and_b32_e32 v227, 0xffff0000, v31
	s_waitcnt lgkmcnt(3)
	v_pk_fma_f32 v[130:131], v[56:57], v[224:225], 0 op_sel_hi:[1,1,0]
	v_pk_fma_f32 v[132:133], v[58:59], v[226:227], 0 op_sel_hi:[1,1,0]
	ds_read_b128 v[56:59], v255 offset:3568
	global_load_dwordx4 v[28:31], v248, s[16:17] offset:1056
	s_waitcnt vmcnt(11)
	v_lshlrev_b32_e32 v224, 16, v32
	v_and_b32_e32 v225, 0xffff0000, v32
	v_lshlrev_b32_e32 v226, 16, v33
	v_and_b32_e32 v227, 0xffff0000, v33
	s_waitcnt lgkmcnt(3)
	v_pk_fma_f32 v[126:127], v[60:61], v[224:225], v[126:127]
	v_pk_fma_f32 v[128:129], v[62:63], v[226:227], v[128:129]
	ds_read_b128 v[60:63], v255 offset:5280
	v_lshlrev_b32_e32 v224, 16, v34
	v_and_b32_e32 v225, 0xffff0000, v34
	v_lshlrev_b32_e32 v226, 16, v35
	v_and_b32_e32 v227, 0xffff0000, v35
	s_waitcnt lgkmcnt(3)
	v_pk_fma_f32 v[130:131], v[220:221], v[224:225], v[130:131]
	v_pk_fma_f32 v[132:133], v[222:223], v[226:227], v[132:133]
	ds_read_b128 v[220:223], v255 offset:5296
	global_load_dwordx4 v[32:35], v249, s[16:17] offset:1056
	s_waitcnt vmcnt(11)
	v_lshlrev_b32_e32 v224, 16, v36
	v_and_b32_e32 v225, 0xffff0000, v36
	v_lshlrev_b32_e32 v226, 16, v37
	v_and_b32_e32 v227, 0xffff0000, v37
	s_waitcnt lgkmcnt(3)
	v_pk_fma_f32 v[126:127], v[48:49], v[224:225], v[126:127]
	v_pk_fma_f32 v[128:129], v[50:51], v[226:227], v[128:129]
	ds_read_b128 v[48:51], v255 offset:576
	v_lshlrev_b32_e32 v224, 16, v38
	v_and_b32_e32 v225, 0xffff0000, v38
	v_lshlrev_b32_e32 v226, 16, v39
	v_and_b32_e32 v227, 0xffff0000, v39
	s_waitcnt lgkmcnt(3)
	v_pk_fma_f32 v[130:131], v[56:57], v[224:225], v[130:131]
	v_pk_fma_f32 v[132:133], v[58:59], v[226:227], v[132:133]
	ds_read_b128 v[56:59], v255 offset:592
	global_load_dwordx4 v[36:39], v253, s[16:17] offset:1056
	s_waitcnt vmcnt(11)
	v_lshlrev_b32_e32 v224, 16, v40
	v_and_b32_e32 v225, 0xffff0000, v40
	v_lshlrev_b32_e32 v226, 16, v41
	v_and_b32_e32 v227, 0xffff0000, v41
	s_waitcnt lgkmcnt(3)
	v_pk_fma_f32 v[126:127], v[60:61], v[224:225], v[126:127]
	v_pk_fma_f32 v[128:129], v[62:63], v[226:227], v[128:129]
	ds_read_b128 v[60:63], v255 offset:2304
	v_lshlrev_b32_e32 v224, 16, v42
	v_and_b32_e32 v225, 0xffff0000, v42
	v_lshlrev_b32_e32 v226, 16, v43
	v_and_b32_e32 v227, 0xffff0000, v43
	s_waitcnt lgkmcnt(3)
	v_pk_fma_f32 v[130:131], v[220:221], v[224:225], v[130:131]
	v_pk_fma_f32 v[132:133], v[222:223], v[226:227], v[132:133]
	ds_read_b128 v[220:223], v255 offset:2320
	global_load_dwordx4 v[40:43], v254, s[16:17] offset:1056
	v_pk_mul_f32 v[224:225], v[126:127], s[18:19] op_sel_hi:[1,0]
	v_pk_mul_f32 v[226:227], v[128:129], s[18:19] op_sel_hi:[1,0]
	v_pk_mul_f32 v[2:3], v[130:131], s[18:19] op_sel_hi:[1,0]
	v_pk_mul_f32 v[134:135], v[132:133], s[18:19] op_sel_hi:[1,0]
	v_exp_f32_e32 v224, v224
	v_exp_f32_e32 v225, v225
	v_exp_f32_e32 v226, v226
	v_exp_f32_e32 v227, v227
	v_exp_f32_e32 v2, v2
	v_exp_f32_e32 v3, v3
	v_exp_f32_e32 v134, v134
	v_exp_f32_e32 v135, v135
	v_pk_add_f32 v[224:225], v[224:225], 1.0 op_sel_hi:[1,0]
	v_pk_add_f32 v[226:227], v[226:227], 1.0 op_sel_hi:[1,0]
	v_pk_add_f32 v[2:3], v[2:3], 1.0 op_sel_hi:[1,0]
	v_pk_add_f32 v[134:135], v[134:135], 1.0 op_sel_hi:[1,0]
	v_rcp_f32_e32 v224, v224
	v_rcp_f32_e32 v225, v225
	v_rcp_f32_e32 v226, v226
	v_rcp_f32_e32 v227, v227
	v_rcp_f32_e32 v2, v2
	v_rcp_f32_e32 v3, v3
	v_rcp_f32_e32 v134, v134
	v_rcp_f32_e32 v135, v135
	v_pk_mul_f32 v[68:69], v[126:127], v[224:225]
	v_pk_mul_f32 v[70:71], v[128:129], v[226:227]
	v_pk_mul_f32 v[122:123], v[130:131], v[2:3]
	v_pk_mul_f32 v[124:125], v[132:133], v[134:135]
	v_pk_mul_f32 v[216:217], v[68:69], v[68:69]
	v_add_f32_e32 v218, v218, v216
	v_add_f32_e32 v218, v217, v218
	v_pk_mul_f32 v[216:217], v[70:71], v[70:71]
	v_add_f32_e32 v218, v218, v216
	v_add_f32_e32 v218, v217, v218
	v_pk_mul_f32 v[216:217], v[122:123], v[122:123]
	v_add_f32_e32 v218, v218, v216
	v_add_f32_e32 v218, v217, v218
	v_pk_mul_f32 v[216:217], v[124:125], v[124:125]
	v_add_f32_e32 v218, v218, v216
	v_add_f32_e32 v218, v217, v218
	s_nop 1
	v_add_f32_dpp v119, v218, v218 quad_perm:[1,0,3,2] row_mask:0xf bank_mask:0xf
	s_nop 1
	v_add_f32_dpp v216, v119, v119 quad_perm:[2,3,0,1] row_mask:0xf bank_mask:0xf
	v_add_f32_e32 v216, 0x358637bd, v216
	v_mul_f32_e32 v119, 0x4b800000, v216
	v_cmp_gt_f32_e32 vcc, 0x800000, v216
	s_nop 1
	v_cndmask_b32_e32 v216, v216, v119, vcc
	v_rsq_f32_e32 v216, v216
	s_nop 0
	v_mul_f32_e32 v119, 0x45800000, v216
	v_cndmask_b32_e32 v216, v216, v119, vcc
	v_mul_f32_e32 v216, 0x3db504f3, v216
	v_pk_mul_f32 v[8:9], v[8:9], v[216:217] op_sel_hi:[1,0]
	v_pk_mul_f32 v[10:11], v[10:11], v[216:217] op_sel_hi:[1,0]
	v_pk_mul_f32 v[12:13], v[12:13], v[216:217] op_sel_hi:[1,0]
	v_pk_mul_f32 v[14:15], v[14:15], v[216:217] op_sel_hi:[1,0]
	v_pk_mul_f32 v[16:17], v[16:17], v[216:217] op_sel_hi:[1,0]
	v_pk_mul_f32 v[18:19], v[18:19], v[216:217] op_sel_hi:[1,0]
	v_pk_mul_f32 v[20:21], v[20:21], v[216:217] op_sel_hi:[1,0]
	v_pk_mul_f32 v[22:23], v[22:23], v[216:217] op_sel_hi:[1,0]
	v_pk_mul_f32 v[24:25], v[24:25], v[216:217] op_sel_hi:[1,0]
	v_pk_mul_f32 v[26:27], v[26:27], v[216:217] op_sel_hi:[1,0]
	v_pk_mul_f32 v[64:65], v[64:65], v[216:217] op_sel_hi:[1,0]
	v_pk_mul_f32 v[66:67], v[66:67], v[216:217] op_sel_hi:[1,0]
	v_pk_mul_f32 v[68:69], v[68:69], v[216:217] op_sel_hi:[1,0]
	v_pk_mul_f32 v[70:71], v[70:71], v[216:217] op_sel_hi:[1,0]
	v_pk_mul_f32 v[122:123], v[122:123], v[216:217] op_sel_hi:[1,0]
	v_pk_mul_f32 v[124:125], v[124:125], v[216:217] op_sel_hi:[1,0]
	v_mov_b32_e32 v218, 0
	v_cvt_pk_bf16_f32 v224, v8, v9
	v_cvt_pk_bf16_f32 v225, v10, v11
	v_cvt_pk_bf16_f32 v226, v12, v13
	v_cvt_pk_bf16_f32 v227, v14, v15
	v_xor_b32_e32 v119, 0, v113
	v_lshl_add_u32 v119, v119, 4, v111
	ds_write_b128 v119, v[224:227] offset:16384
	v_pk_mul_f32 v[2:3], v[230:231], v[8:9] op_sel_hi:[0,1]
	v_pk_mul_f32 v[134:135], v[230:231], v[10:11] op_sel_hi:[0,1]
	v_cvt_pk_bf16_f32 v224, v2, v3
	v_cvt_pk_bf16_f32 v225, v134, v135
	v_pk_mul_f32 v[2:3], v[230:231], v[12:13] op_sel_hi:[0,1]
	v_pk_mul_f32 v[134:135], v[230:231], v[14:15] op_sel_hi:[0,1]
	v_cvt_pk_bf16_f32 v226, v2, v3
	v_cvt_pk_bf16_f32 v227, v134, v135
	global_store_dwordx4 v117, v[224:227], s[92:93] offset:0
	s_nop 1
	v_cvt_pk_bf16_f32 v224, v16, v17
	v_cvt_pk_bf16_f32 v225, v18, v19
	v_cvt_pk_bf16_f32 v226, v20, v21
	v_cvt_pk_bf16_f32 v227, v22, v23
	v_xor_b32_e32 v119, 1, v113
	v_lshl_add_u32 v119, v119, 4, v111
	ds_write_b128 v119, v[224:227] offset:16384
	v_pk_mul_f32 v[2:3], v[230:231], v[16:17] op_sel_hi:[0,1]
	v_pk_mul_f32 v[134:135], v[230:231], v[18:19] op_sel_hi:[0,1]
	v_cvt_pk_bf16_f32 v224, v2, v3
	v_cvt_pk_bf16_f32 v225, v134, v135
	v_pk_mul_f32 v[2:3], v[230:231], v[20:21] op_sel_hi:[0,1]
	v_pk_mul_f32 v[134:135], v[230:231], v[22:23] op_sel_hi:[0,1]
	v_cvt_pk_bf16_f32 v226, v2, v3
	v_cvt_pk_bf16_f32 v227, v134, v135
	global_store_dwordx4 v117, v[224:227], s[92:93] offset:16
	s_nop 1
	v_cvt_pk_bf16_f32 v224, v24, v25
	v_cvt_pk_bf16_f32 v225, v26, v27
	v_cvt_pk_bf16_f32 v226, v64, v65
	v_cvt_pk_bf16_f32 v227, v66, v67
	v_xor_b32_e32 v119, 2, v113
	v_lshl_add_u32 v119, v119, 4, v111
	ds_write_b128 v119, v[224:227] offset:16384
	v_pk_mul_f32 v[2:3], v[230:231], v[24:25] op_sel_hi:[0,1]
	v_pk_mul_f32 v[134:135], v[230:231], v[26:27] op_sel_hi:[0,1]
	v_cvt_pk_bf16_f32 v224, v2, v3
	v_cvt_pk_bf16_f32 v225, v134, v135
	v_pk_mul_f32 v[2:3], v[230:231], v[64:65] op_sel_hi:[0,1]
	v_pk_mul_f32 v[134:135], v[230:231], v[66:67] op_sel_hi:[0,1]
	v_cvt_pk_bf16_f32 v226, v2, v3
	v_cvt_pk_bf16_f32 v227, v134, v135
	global_store_dwordx4 v117, v[224:227], s[92:93] offset:32
	s_nop 1
	v_cvt_pk_bf16_f32 v224, v68, v69
	v_cvt_pk_bf16_f32 v225, v70, v71
	v_cvt_pk_bf16_f32 v226, v122, v123
	v_cvt_pk_bf16_f32 v227, v124, v125
	v_xor_b32_e32 v119, 3, v113
	v_lshl_add_u32 v119, v119, 4, v111
	ds_write_b128 v119, v[224:227] offset:16384
	v_pk_mul_f32 v[2:3], v[230:231], v[68:69] op_sel_hi:[0,1]
	v_pk_mul_f32 v[134:135], v[230:231], v[70:71] op_sel_hi:[0,1]
	v_cvt_pk_bf16_f32 v224, v2, v3
	v_cvt_pk_bf16_f32 v225, v134, v135
	v_pk_mul_f32 v[2:3], v[230:231], v[122:123] op_sel_hi:[0,1]
	v_pk_mul_f32 v[134:135], v[230:231], v[124:125] op_sel_hi:[0,1]
	v_cvt_pk_bf16_f32 v226, v2, v3
	v_cvt_pk_bf16_f32 v227, v134, v135
	global_store_dwordx4 v117, v[224:227], s[92:93] offset:48
	s_nop 1
	s_cmp_lg_u32 s15, 0
	s_cbranch_scc1 .Lpb_sk_4
	s_waitcnt vmcnt(13)
	v_cndmask_b32_e64 v44, 0, v44, s[70:71]
	v_cndmask_b32_e64 v45, 0, v45, s[70:71]
	v_cndmask_b32_e64 v46, 0, v46, s[70:71]
	v_cndmask_b32_e64 v47, 0, v47, s[70:71]
	v_cndmask_b32_e64 v52, 0, v52, s[72:73]
	v_cndmask_b32_e64 v53, 0, v53, s[72:73]
	v_cndmask_b32_e64 v54, 0, v54, s[72:73]
	v_cndmask_b32_e64 v55, 0, v55, s[72:73]
	v_cndmask_b32_e64 v168, 0, v168, s[74:75]
	v_cndmask_b32_e64 v169, 0, v169, s[74:75]
	v_cndmask_b32_e64 v170, 0, v170, s[74:75]
	v_cndmask_b32_e64 v171, 0, v171, s[74:75]
.Lpb_sk_4:
	s_waitcnt vmcnt(15)
	v_lshlrev_b32_e32 v224, 16, v44
	v_and_b32_e32 v225, 0xffff0000, v44
	v_lshlrev_b32_e32 v226, 16, v45
	v_and_b32_e32 v227, 0xffff0000, v45
	s_waitcnt lgkmcnt(7)
	v_pk_fma_f32 v[126:127], v[48:49], v[224:225], 0 op_sel_hi:[1,1,0]
	v_pk_fma_f32 v[128:129], v[50:51], v[226:227], 0 op_sel_hi:[1,1,0]
	ds_read_b128 v[48:51], v255 offset:4032
	v_lshlrev_b32_e32 v224, 16, v46
	v_and_b32_e32 v225, 0xffff0000, v46
	v_lshlrev_b32_e32 v226, 16, v47
	v_and_b32_e32 v227, 0xffff0000, v47
	s_waitcnt lgkmcnt(7)
	v_pk_fma_f32 v[130:131], v[56:57], v[224:225], 0 op_sel_hi:[1,1,0]
	v_pk_fma_f32 v[132:133], v[58:59], v[226:227], 0 op_sel_hi:[1,1,0]
	ds_read_b128 v[56:59], v255 offset:4048
	global_load_dwordx4 v[44:47], v248, s[16:17] offset:1072
	s_waitcnt vmcnt(15)
	v_lshlrev_b32_e32 v224, 16, v52
	v_and_b32_e32 v225, 0xffff0000, v52
	v_lshlrev_b32_e32 v226, 16, v53
	v_and_b32_e32 v227, 0xffff0000, v53
	s_waitcnt lgkmcnt(7)
	v_pk_fma_f32 v[126:127], v[60:61], v[224:225], v[126:127]
	v_pk_fma_f32 v[128:129], v[62:63], v[226:227], v[128:129]
	ds_read_b128 v[60:63], v255 offset:5760
	v_lshlrev_b32_e32 v224, 16, v54
	v_and_b32_e32 v225, 0xffff0000, v54
	v_lshlrev_b32_e32 v226, 16, v55
	v_and_b32_e32 v227, 0xffff0000, v55
	s_waitcnt lgkmcnt(7)
	v_pk_fma_f32 v[130:131], v[220:221], v[224:225], v[130:131]
	v_pk_fma_f32 v[132:133], v[222:223], v[226:227], v[132:133]
	ds_read_b128 v[220:223], v255 offset:5776
	global_load_dwordx4 v[52:55], v249, s[16:17] offset:1072
	s_waitcnt vmcnt(15)
	v_lshlrev_b32_e32 v224, 16, v168
	v_and_b32_e32 v225, 0xffff0000, v168
	v_lshlrev_b32_e32 v226, 16, v169
	v_and_b32_e32 v227, 0xffff0000, v169
	s_waitcnt lgkmcnt(3)
	v_pk_fma_f32 v[126:127], v[48:49], v[224:225], v[126:127]
	v_pk_fma_f32 v[128:129], v[50:51], v[226:227], v[128:129]
	ds_read_b128 v[48:51], v255 offset:608
	v_lshlrev_b32_e32 v224, 16, v170
	v_and_b32_e32 v225, 0xffff0000, v170
	v_lshlrev_b32_e32 v226, 16, v171
	v_and_b32_e32 v227, 0xffff0000, v171
	s_waitcnt lgkmcnt(3)
	v_pk_fma_f32 v[130:131], v[56:57], v[224:225], v[130:131]
	v_pk_fma_f32 v[132:133], v[58:59], v[226:227], v[132:133]
	ds_read_b128 v[56:59], v255 offset:624
	global_load_dwordx4 v[168:171], v253, s[16:17] offset:1072
	s_waitcnt vmcnt(15)
	v_lshlrev_b32_e32 v224, 16, v172
	v_and_b32_e32 v225, 0xffff0000, v172
	v_lshlrev_b32_e32 v226, 16, v173
	v_and_b32_e32 v227, 0xffff0000, v173
	s_waitcnt lgkmcnt(3)
	v_pk_fma_f32 v[126:127], v[60:61], v[224:225], v[126:127]
	v_pk_fma_f32 v[128:129], v[62:63], v[226:227], v[128:129]
	ds_read_b128 v[60:63], v255 offset:2336
	v_lshlrev_b32_e32 v224, 16, v174
	v_and_b32_e32 v225, 0xffff0000, v174
	v_lshlrev_b32_e32 v226, 16, v175
	v_and_b32_e32 v227, 0xffff0000, v175
	s_waitcnt lgkmcnt(3)
	v_pk_fma_f32 v[130:131], v[220:221], v[224:225], v[130:131]
	v_pk_fma_f32 v[132:133], v[222:223], v[226:227], v[132:133]
	ds_read_b128 v[220:223], v255 offset:2352
	global_load_dwordx4 v[172:175], v254, s[16:17] offset:1072
	v_pk_mul_f32 v[224:225], v[126:127], s[18:19] op_sel_hi:[1,0]
	v_pk_mul_f32 v[226:227], v[128:129], s[18:19] op_sel_hi:[1,0]
	v_pk_mul_f32 v[2:3], v[130:131], s[18:19] op_sel_hi:[1,0]
	v_pk_mul_f32 v[134:135], v[132:133], s[18:19] op_sel_hi:[1,0]
	v_exp_f32_e32 v224, v224
	v_exp_f32_e32 v225, v225
	v_exp_f32_e32 v226, v226
	v_exp_f32_e32 v227, v227
	v_exp_f32_e32 v2, v2
	v_exp_f32_e32 v3, v3
	v_exp_f32_e32 v134, v134
	v_exp_f32_e32 v135, v135
	v_pk_add_f32 v[224:225], v[224:225], 1.0 op_sel_hi:[1,0]
	v_pk_add_f32 v[226:227], v[226:227], 1.0 op_sel_hi:[1,0]
	v_pk_add_f32 v[2:3], v[2:3], 1.0 op_sel_hi:[1,0]
	v_pk_add_f32 v[134:135], v[134:135], 1.0 op_sel_hi:[1,0]
	v_rcp_f32_e32 v224, v224
	v_rcp_f32_e32 v225, v225
	v_rcp_f32_e32 v226, v226
	v_rcp_f32_e32 v227, v227
	v_rcp_f32_e32 v2, v2
	v_rcp_f32_e32 v3, v3
	v_rcp_f32_e32 v134, v134
	v_rcp_f32_e32 v135, v135
	v_pk_mul_f32 v[8:9], v[126:127], v[224:225]
	v_pk_mul_f32 v[10:11], v[128:129], v[226:227]
	v_pk_mul_f32 v[12:13], v[130:131], v[2:3]
	v_pk_mul_f32 v[14:15], v[132:133], v[134:135]
	v_pk_mul_f32 v[216:217], v[8:9], v[8:9]
	v_add_f32_e32 v218, v218, v216
	v_add_f32_e32 v218, v217, v218
	v_pk_mul_f32 v[216:217], v[10:11], v[10:11]
	v_add_f32_e32 v218, v218, v216
	v_add_f32_e32 v218, v217, v218
	v_pk_mul_f32 v[216:217], v[12:13], v[12:13]
	v_add_f32_e32 v218, v218, v216
	v_add_f32_e32 v218, v217, v218
	v_pk_mul_f32 v[216:217], v[14:15], v[14:15]
	v_add_f32_e32 v218, v218, v216
	v_add_f32_e32 v218, v217, v218
	s_cmp_lg_u32 s15, 0
	s_cbranch_scc1 .Lpb_sk_5
	s_waitcnt vmcnt(13)
	v_cndmask_b32_e64 v176, 0, v176, s[70:71]
	v_cndmask_b32_e64 v177, 0, v177, s[70:71]
	v_cndmask_b32_e64 v178, 0, v178, s[70:71]
	v_cndmask_b32_e64 v179, 0, v179, s[70:71]
	v_cndmask_b32_e64 v180, 0, v180, s[72:73]
	v_cndmask_b32_e64 v181, 0, v181, s[72:73]
	v_cndmask_b32_e64 v182, 0, v182, s[72:73]
	v_cndmask_b32_e64 v183, 0, v183, s[72:73]
	v_cndmask_b32_e64 v198, 0, v198, s[74:75]
	v_cndmask_b32_e64 v199, 0, v199, s[74:75]
	v_cndmask_b32_e64 v200, 0, v200, s[74:75]
	v_cndmask_b32_e64 v201, 0, v201, s[74:75]
.Lpb_sk_5:
	s_waitcnt vmcnt(15)
	v_lshlrev_b32_e32 v224, 16, v176
	v_and_b32_e32 v225, 0xffff0000, v176
	v_lshlrev_b32_e32 v226, 16, v177
	v_and_b32_e32 v227, 0xffff0000, v177
	s_waitcnt lgkmcnt(3)
	v_pk_fma_f32 v[126:127], v[48:49], v[224:225], 0 op_sel_hi:[1,1,0]
	v_pk_fma_f32 v[128:129], v[50:51], v[226:227], 0 op_sel_hi:[1,1,0]
	ds_read_b128 v[48:51], v255 offset:4064
	v_lshlrev_b32_e32 v224, 16, v178
	v_and_b32_e32 v225, 0xffff0000, v178
	v_lshlrev_b32_e32 v226, 16, v179
	v_and_b32_e32 v227, 0xffff0000, v179
	s_waitcnt lgkmcnt(3)
	v_pk_fma_f32 v[130:131], v[56:57], v[224:225], 0 op_sel_hi:[1,1,0]
	v_pk_fma_f32 v[132:133], v[58:59], v[226:227], 0 op_sel_hi:[1,1,0]
	ds_read_b128 v[56:59], v255 offset:4080
	global_load_dwordx4 v[176:179], v248, s[16:17] offset:2048
	s_waitcnt vmcnt(15)
	v_lshlrev_b32_e32 v224, 16, v180
	v_and_b32_e32 v225, 0xffff0000, v180
	v_lshlrev_b32_e32 v226, 16, v181
	v_and_b32_e32 v227, 0xffff0000, v181
	s_waitcnt lgkmcnt(3)
	v_pk_fma_f32 v[126:127], v[60:61], v[224:225], v[126:127]
	v_pk_fma_f32 v[128:129], v[62:63], v[226:227], v[128:129]
	ds_read_b128 v[60:63], v255 offset:5792
	v_lshlrev_b32_e32 v224, 16, v182
	v_and_b32_e32 v225, 0xffff0000, v182
	v_lshlrev_b32_e32 v226, 16, v183
	v_and_b32_e32 v227, 0xffff0000, v183
	s_waitcnt lgkmcnt(3)
	v_pk_fma_f32 v[130:131], v[220:221], v[224:225], v[130:131]
	v_pk_fma_f32 v[132:133], v[222:223], v[226:227], v[132:133]
	ds_read_b128 v[220:223], v255 offset:5808
	global_load_dwordx4 v[180:183], v249, s[16:17] offset:2048
	s_waitcnt vmcnt(15)
	v_lshlrev_b32_e32 v224, 16, v198
	v_and_b32_e32 v225, 0xffff0000, v198
	v_lshlrev_b32_e32 v226, 16, v199
	v_and_b32_e32 v227, 0xffff0000, v199
	s_waitcnt lgkmcnt(3)
	v_pk_fma_f32 v[126:127], v[48:49], v[224:225], v[126:127]
	v_pk_fma_f32 v[128:129], v[50:51], v[226:227], v[128:129]
	ds_read_b128 v[48:51], v255 offset:640
	v_lshlrev_b32_e32 v224, 16, v200
	v_and_b32_e32 v225, 0xffff0000, v200
	v_lshlrev_b32_e32 v226, 16, v201
	v_and_b32_e32 v227, 0xffff0000, v201
	s_waitcnt lgkmcnt(3)
	v_pk_fma_f32 v[130:131], v[56:57], v[224:225], v[130:131]
	v_pk_fma_f32 v[132:133], v[58:59], v[226:227], v[132:133]
	ds_read_b128 v[56:59], v255 offset:656
	global_load_dwordx4 v[198:201], v253, s[16:17] offset:2048
	s_waitcnt vmcnt(15)
	v_lshlrev_b32_e32 v224, 16, v210
	v_and_b32_e32 v225, 0xffff0000, v210
	v_lshlrev_b32_e32 v226, 16, v211
	v_and_b32_e32 v227, 0xffff0000, v211
	s_waitcnt lgkmcnt(3)
	v_pk_fma_f32 v[126:127], v[60:61], v[224:225], v[126:127]
	v_pk_fma_f32 v[128:129], v[62:63], v[226:227], v[128:129]
	ds_read_b128 v[60:63], v255 offset:2368
	v_lshlrev_b32_e32 v224, 16, v212
	v_and_b32_e32 v225, 0xffff0000, v212
	v_lshlrev_b32_e32 v226, 16, v213
	v_and_b32_e32 v227, 0xffff0000, v213
	s_waitcnt lgkmcnt(3)
	v_pk_fma_f32 v[130:131], v[220:221], v[224:225], v[130:131]
	v_pk_fma_f32 v[132:133], v[222:223], v[226:227], v[132:133]
	ds_read_b128 v[220:223], v255 offset:2384
	global_load_dwordx4 v[210:213], v254, s[16:17] offset:2048
	v_pk_mul_f32 v[224:225], v[126:127], s[18:19] op_sel_hi:[1,0]
	v_pk_mul_f32 v[226:227], v[128:129], s[18:19] op_sel_hi:[1,0]
	v_pk_mul_f32 v[2:3], v[130:131], s[18:19] op_sel_hi:[1,0]
	v_pk_mul_f32 v[134:135], v[132:133], s[18:19] op_sel_hi:[1,0]
	v_exp_f32_e32 v224, v224
	v_exp_f32_e32 v225, v225
	v_exp_f32_e32 v226, v226
	v_exp_f32_e32 v227, v227
	v_exp_f32_e32 v2, v2
	v_exp_f32_e32 v3, v3
	v_exp_f32_e32 v134, v134
	v_exp_f32_e32 v135, v135
	v_pk_add_f32 v[224:225], v[224:225], 1.0 op_sel_hi:[1,0]
	v_pk_add_f32 v[226:227], v[226:227], 1.0 op_sel_hi:[1,0]
	v_pk_add_f32 v[2:3], v[2:3], 1.0 op_sel_hi:[1,0]
	v_pk_add_f32 v[134:135], v[134:135], 1.0 op_sel_hi:[1,0]
	v_rcp_f32_e32 v224, v224
	v_rcp_f32_e32 v225, v225
	v_rcp_f32_e32 v226, v226
	v_rcp_f32_e32 v227, v227
	v_rcp_f32_e32 v2, v2
	v_rcp_f32_e32 v3, v3
	v_rcp_f32_e32 v134, v134
	v_rcp_f32_e32 v135, v135
	v_pk_mul_f32 v[16:17], v[126:127], v[224:225]
	v_pk_mul_f32 v[18:19], v[128:129], v[226:227]
	v_pk_mul_f32 v[20:21], v[130:131], v[2:3]
	v_pk_mul_f32 v[22:23], v[132:133], v[134:135]
	v_pk_mul_f32 v[216:217], v[16:17], v[16:17]
	v_add_f32_e32 v218, v218, v216
	v_add_f32_e32 v218, v217, v218
	v_pk_mul_f32 v[216:217], v[18:19], v[18:19]
	v_add_f32_e32 v218, v218, v216
	v_add_f32_e32 v218, v217, v218
	v_pk_mul_f32 v[216:217], v[20:21], v[20:21]
	v_add_f32_e32 v218, v218, v216
	v_add_f32_e32 v218, v217, v218
	v_pk_mul_f32 v[216:217], v[22:23], v[22:23]
	v_add_f32_e32 v218, v218, v216
	v_add_f32_e32 v218, v217, v218
	s_cmp_lg_u32 s15, 0
	s_cbranch_scc1 .Lpb_sk_6
	s_waitcnt vmcnt(13)
	v_cndmask_b32_e64 v28, 0, v28, s[70:71]
	v_cndmask_b32_e64 v29, 0, v29, s[70:71]
	v_cndmask_b32_e64 v30, 0, v30, s[70:71]
	v_cndmask_b32_e64 v31, 0, v31, s[70:71]
	v_cndmask_b32_e64 v32, 0, v32, s[72:73]
	v_cndmask_b32_e64 v33, 0, v33, s[72:73]
	v_cndmask_b32_e64 v34, 0, v34, s[72:73]
	v_cndmask_b32_e64 v35, 0, v35, s[72:73]
	v_cndmask_b32_e64 v36, 0, v36, s[74:75]
	v_cndmask_b32_e64 v37, 0, v37, s[74:75]
	v_cndmask_b32_e64 v38, 0, v38, s[74:75]
	v_cndmask_b32_e64 v39, 0, v39, s[74:75]
.Lpb_sk_6:
	s_waitcnt vmcnt(15)
	v_lshlrev_b32_e32 v224, 16, v28
	v_and_b32_e32 v225, 0xffff0000, v28
	v_lshlrev_b32_e32 v226, 16, v29
	v_and_b32_e32 v227, 0xffff0000, v29
	s_waitcnt lgkmcnt(3)
	v_pk_fma_f32 v[126:127], v[48:49], v[224:225], 0 op_sel_hi:[1,1,0]
	v_pk_fma_f32 v[128:129], v[50:51], v[226:227], 0 op_sel_hi:[1,1,0]
	ds_read_b128 v[48:51], v255 offset:4096
	v_lshlrev_b32_e32 v224, 16, v30
	v_and_b32_e32 v225, 0xffff0000, v30
	v_lshlrev_b32_e32 v226, 16, v31
	v_and_b32_e32 v227, 0xffff0000, v31
	s_waitcnt lgkmcnt(3)
	v_pk_fma_f32 v[130:131], v[56:57], v[224:225], 0 op_sel_hi:[1,1,0]
	v_pk_fma_f32 v[132:133], v[58:59], v[226:227], 0 op_sel_hi:[1,1,0]
	ds_read_b128 v[56:59], v255 offset:4112
	global_load_dwordx4 v[28:31], v248, s[16:17] offset:2064
	s_waitcnt vmcnt(15)
	v_lshlrev_b32_e32 v224, 16, v32
	v_and_b32_e32 v225, 0xffff0000, v32
	v_lshlrev_b32_e32 v226, 16, v33
	v_and_b32_e32 v227, 0xffff0000, v33
	s_waitcnt lgkmcnt(3)
	v_pk_fma_f32 v[126:127], v[60:61], v[224:225], v[126:127]
	v_pk_fma_f32 v[128:129], v[62:63], v[226:227], v[128:129]
	ds_read_b128 v[60:63], v255 offset:5824
	v_lshlrev_b32_e32 v224, 16, v34
	v_and_b32_e32 v225, 0xffff0000, v34
	v_lshlrev_b32_e32 v226, 16, v35
	v_and_b32_e32 v227, 0xffff0000, v35
	s_waitcnt lgkmcnt(3)
	v_pk_fma_f32 v[130:131], v[220:221], v[224:225], v[130:131]
	v_pk_fma_f32 v[132:133], v[222:223], v[226:227], v[132:133]
	ds_read_b128 v[220:223], v255 offset:5840
	global_load_dwordx4 v[32:35], v249, s[16:17] offset:2064
	s_waitcnt vmcnt(15)
	v_lshlrev_b32_e32 v224, 16, v36
	v_and_b32_e32 v225, 0xffff0000, v36
	v_lshlrev_b32_e32 v226, 16, v37
	v_and_b32_e32 v227, 0xffff0000, v37
	s_waitcnt lgkmcnt(3)
	v_pk_fma_f32 v[126:127], v[48:49], v[224:225], v[126:127]
	v_pk_fma_f32 v[128:129], v[50:51], v[226:227], v[128:129]
	ds_read_b128 v[48:51], v255 offset:672
	v_lshlrev_b32_e32 v224, 16, v38
	v_and_b32_e32 v225, 0xffff0000, v38
	v_lshlrev_b32_e32 v226, 16, v39
	v_and_b32_e32 v227, 0xffff0000, v39
	s_waitcnt lgkmcnt(3)
	v_pk_fma_f32 v[130:131], v[56:57], v[224:225], v[130:131]
	v_pk_fma_f32 v[132:133], v[58:59], v[226:227], v[132:133]
	ds_read_b128 v[56:59], v255 offset:688
	global_load_dwordx4 v[36:39], v253, s[16:17] offset:2064
	s_waitcnt vmcnt(15)
	v_lshlrev_b32_e32 v224, 16, v40
	v_and_b32_e32 v225, 0xffff0000, v40
	v_lshlrev_b32_e32 v226, 16, v41
	v_and_b32_e32 v227, 0xffff0000, v41
	s_waitcnt lgkmcnt(3)
	v_pk_fma_f32 v[126:127], v[60:61], v[224:225], v[126:127]
	v_pk_fma_f32 v[128:129], v[62:63], v[226:227], v[128:129]
	ds_read_b128 v[60:63], v255 offset:2400
	v_lshlrev_b32_e32 v224, 16, v42
	v_and_b32_e32 v225, 0xffff0000, v42
	v_lshlrev_b32_e32 v226, 16, v43
	v_and_b32_e32 v227, 0xffff0000, v43
	s_waitcnt lgkmcnt(3)
	v_pk_fma_f32 v[130:131], v[220:221], v[224:225], v[130:131]
	v_pk_fma_f32 v[132:133], v[222:223], v[226:227], v[132:133]
	ds_read_b128 v[220:223], v255 offset:2416
	global_load_dwordx4 v[40:43], v254, s[16:17] offset:2064
	v_pk_mul_f32 v[224:225], v[126:127], s[18:19] op_sel_hi:[1,0]
	v_pk_mul_f32 v[226:227], v[128:129], s[18:19] op_sel_hi:[1,0]
	v_pk_mul_f32 v[2:3], v[130:131], s[18:19] op_sel_hi:[1,0]
	v_pk_mul_f32 v[134:135], v[132:133], s[18:19] op_sel_hi:[1,0]
	v_exp_f32_e32 v224, v224
	v_exp_f32_e32 v225, v225
	v_exp_f32_e32 v226, v226
	v_exp_f32_e32 v227, v227
	v_exp_f32_e32 v2, v2
	v_exp_f32_e32 v3, v3
	v_exp_f32_e32 v134, v134
	v_exp_f32_e32 v135, v135
	v_pk_add_f32 v[224:225], v[224:225], 1.0 op_sel_hi:[1,0]
	v_pk_add_f32 v[226:227], v[226:227], 1.0 op_sel_hi:[1,0]
	v_pk_add_f32 v[2:3], v[2:3], 1.0 op_sel_hi:[1,0]
	v_pk_add_f32 v[134:135], v[134:135], 1.0 op_sel_hi:[1,0]
	v_rcp_f32_e32 v224, v224
	v_rcp_f32_e32 v225, v225
	v_rcp_f32_e32 v226, v226
	v_rcp_f32_e32 v227, v227
	v_rcp_f32_e32 v2, v2
	v_rcp_f32_e32 v3, v3
	v_rcp_f32_e32 v134, v134
	v_rcp_f32_e32 v135, v135
	v_pk_mul_f32 v[24:25], v[126:127], v[224:225]
	v_pk_mul_f32 v[26:27], v[128:129], v[226:227]
	v_pk_mul_f32 v[64:65], v[130:131], v[2:3]
	v_pk_mul_f32 v[66:67], v[132:133], v[134:135]
	v_pk_mul_f32 v[216:217], v[24:25], v[24:25]
	v_add_f32_e32 v218, v218, v216
	v_add_f32_e32 v218, v217, v218
	v_pk_mul_f32 v[216:217], v[26:27], v[26:27]
	v_add_f32_e32 v218, v218, v216
	v_add_f32_e32 v218, v217, v218
	v_pk_mul_f32 v[216:217], v[64:65], v[64:65]
	v_add_f32_e32 v218, v218, v216
	v_add_f32_e32 v218, v217, v218
	v_pk_mul_f32 v[216:217], v[66:67], v[66:67]
	v_add_f32_e32 v218, v218, v216
	v_add_f32_e32 v218, v217, v218
	s_cmp_lg_u32 s15, 0
	s_cbranch_scc1 .Lpb_sk_7
	s_waitcnt vmcnt(9)
	v_cndmask_b32_e64 v44, 0, v44, s[70:71]
	v_cndmask_b32_e64 v45, 0, v45, s[70:71]
	v_cndmask_b32_e64 v46, 0, v46, s[70:71]
	v_cndmask_b32_e64 v47, 0, v47, s[70:71]
	v_cndmask_b32_e64 v52, 0, v52, s[72:73]
	v_cndmask_b32_e64 v53, 0, v53, s[72:73]
	v_cndmask_b32_e64 v54, 0, v54, s[72:73]
	v_cndmask_b32_e64 v55, 0, v55, s[72:73]
	v_cndmask_b32_e64 v168, 0, v168, s[74:75]
	v_cndmask_b32_e64 v169, 0, v169, s[74:75]
	v_cndmask_b32_e64 v170, 0, v170, s[74:75]
	v_cndmask_b32_e64 v171, 0, v171, s[74:75]
.Lpb_sk_7:
	s_waitcnt vmcnt(11)
	v_lshlrev_b32_e32 v224, 16, v44
	v_and_b32_e32 v225, 0xffff0000, v44
	v_lshlrev_b32_e32 v226, 16, v45
	v_and_b32_e32 v227, 0xffff0000, v45
	s_waitcnt lgkmcnt(3)
	v_pk_fma_f32 v[126:127], v[48:49], v[224:225], 0 op_sel_hi:[1,1,0]
	v_pk_fma_f32 v[128:129], v[50:51], v[226:227], 0 op_sel_hi:[1,1,0]
	ds_read_b128 v[48:51], v255 offset:4128
	v_lshlrev_b32_e32 v224, 16, v46
	v_and_b32_e32 v225, 0xffff0000, v46
	v_lshlrev_b32_e32 v226, 16, v47
	v_and_b32_e32 v227, 0xffff0000, v47
	s_waitcnt lgkmcnt(3)
	v_pk_fma_f32 v[130:131], v[56:57], v[224:225], 0 op_sel_hi:[1,1,0]
	v_pk_fma_f32 v[132:133], v[58:59], v[226:227], 0 op_sel_hi:[1,1,0]
	ds_read_b128 v[56:59], v255 offset:4144
	global_load_dwordx4 v[44:47], v248, s[16:17] offset:2080
	s_waitcnt vmcnt(11)
	v_lshlrev_b32_e32 v224, 16, v52
	v_and_b32_e32 v225, 0xffff0000, v52
	v_lshlrev_b32_e32 v226, 16, v53
	v_and_b32_e32 v227, 0xffff0000, v53
	s_waitcnt lgkmcnt(3)
	v_pk_fma_f32 v[126:127], v[60:61], v[224:225], v[126:127]
	v_pk_fma_f32 v[128:129], v[62:63], v[226:227], v[128:129]
	ds_read_b128 v[60:63], v255 offset:5856
	v_lshlrev_b32_e32 v224, 16, v54
	v_and_b32_e32 v225, 0xffff0000, v54
	v_lshlrev_b32_e32 v226, 16, v55
	v_and_b32_e32 v227, 0xffff0000, v55
	s_waitcnt lgkmcnt(3)
	v_pk_fma_f32 v[130:131], v[220:221], v[224:225], v[130:131]
	v_pk_fma_f32 v[132:133], v[222:223], v[226:227], v[132:133]
	ds_read_b128 v[220:223], v255 offset:5872
	global_load_dwordx4 v[52:55], v249, s[16:17] offset:2080
	s_waitcnt vmcnt(11)
	v_lshlrev_b32_e32 v224, 16, v168
	v_and_b32_e32 v225, 0xffff0000, v168
	v_lshlrev_b32_e32 v226, 16, v169
	v_and_b32_e32 v227, 0xffff0000, v169
	s_waitcnt lgkmcnt(3)
	v_pk_fma_f32 v[126:127], v[48:49], v[224:225], v[126:127]
	v_pk_fma_f32 v[128:129], v[50:51], v[226:227], v[128:129]
	ds_read_b128 v[48:51], v255 offset:1152
	v_lshlrev_b32_e32 v224, 16, v170
	v_and_b32_e32 v225, 0xffff0000, v170
	v_lshlrev_b32_e32 v226, 16, v171
	v_and_b32_e32 v227, 0xffff0000, v171
	s_waitcnt lgkmcnt(3)
	v_pk_fma_f32 v[130:131], v[56:57], v[224:225], v[130:131]
	v_pk_fma_f32 v[132:133], v[58:59], v[226:227], v[132:133]
	ds_read_b128 v[56:59], v255 offset:1168
	global_load_dwordx4 v[168:171], v253, s[16:17] offset:2080
	s_waitcnt vmcnt(11)
	v_lshlrev_b32_e32 v224, 16, v172
	v_and_b32_e32 v225, 0xffff0000, v172
	v_lshlrev_b32_e32 v226, 16, v173
	v_and_b32_e32 v227, 0xffff0000, v173
	s_waitcnt lgkmcnt(3)
	v_pk_fma_f32 v[126:127], v[60:61], v[224:225], v[126:127]
	v_pk_fma_f32 v[128:129], v[62:63], v[226:227], v[128:129]
	ds_read_b128 v[60:63], v255 offset:2880
	v_lshlrev_b32_e32 v224, 16, v174
	v_and_b32_e32 v225, 0xffff0000, v174
	v_lshlrev_b32_e32 v226, 16, v175
	v_and_b32_e32 v227, 0xffff0000, v175
	s_waitcnt lgkmcnt(3)
	v_pk_fma_f32 v[130:131], v[220:221], v[224:225], v[130:131]
	v_pk_fma_f32 v[132:133], v[222:223], v[226:227], v[132:133]
	ds_read_b128 v[220:223], v255 offset:2896
	global_load_dwordx4 v[172:175], v254, s[16:17] offset:2080
	v_pk_mul_f32 v[224:225], v[126:127], s[18:19] op_sel_hi:[1,0]
	v_pk_mul_f32 v[226:227], v[128:129], s[18:19] op_sel_hi:[1,0]
	v_pk_mul_f32 v[2:3], v[130:131], s[18:19] op_sel_hi:[1,0]
	v_pk_mul_f32 v[134:135], v[132:133], s[18:19] op_sel_hi:[1,0]
	v_exp_f32_e32 v224, v224
	v_exp_f32_e32 v225, v225
	v_exp_f32_e32 v226, v226
	v_exp_f32_e32 v227, v227
	v_exp_f32_e32 v2, v2
	v_exp_f32_e32 v3, v3
	v_exp_f32_e32 v134, v134
	v_exp_f32_e32 v135, v135
	v_pk_add_f32 v[224:225], v[224:225], 1.0 op_sel_hi:[1,0]
	v_pk_add_f32 v[226:227], v[226:227], 1.0 op_sel_hi:[1,0]
	v_pk_add_f32 v[2:3], v[2:3], 1.0 op_sel_hi:[1,0]
	v_pk_add_f32 v[134:135], v[134:135], 1.0 op_sel_hi:[1,0]
	v_rcp_f32_e32 v224, v224
	v_rcp_f32_e32 v225, v225
	v_rcp_f32_e32 v226, v226
	v_rcp_f32_e32 v227, v227
	v_rcp_f32_e32 v2, v2
	v_rcp_f32_e32 v3, v3
	v_rcp_f32_e32 v134, v134
	v_rcp_f32_e32 v135, v135
	v_pk_mul_f32 v[68:69], v[126:127], v[224:225]
	v_pk_mul_f32 v[70:71], v[128:129], v[226:227]
	v_pk_mul_f32 v[122:123], v[130:131], v[2:3]
	v_pk_mul_f32 v[124:125], v[132:133], v[134:135]
	v_pk_mul_f32 v[216:217], v[68:69], v[68:69]
	v_add_f32_e32 v218, v218, v216
	v_add_f32_e32 v218, v217, v218
	v_pk_mul_f32 v[216:217], v[70:71], v[70:71]
	v_add_f32_e32 v218, v218, v216
	v_add_f32_e32 v218, v217, v218
	v_pk_mul_f32 v[216:217], v[122:123], v[122:123]
	v_add_f32_e32 v218, v218, v216
	v_add_f32_e32 v218, v217, v218
	v_pk_mul_f32 v[216:217], v[124:125], v[124:125]
	v_add_f32_e32 v218, v218, v216
	v_add_f32_e32 v218, v217, v218
	s_nop 1
	v_add_f32_dpp v119, v218, v218 quad_perm:[1,0,3,2] row_mask:0xf bank_mask:0xf
	s_nop 1
	v_add_f32_dpp v216, v119, v119 quad_perm:[2,3,0,1] row_mask:0xf bank_mask:0xf
	v_add_f32_e32 v216, 0x358637bd, v216
	v_mul_f32_e32 v119, 0x4b800000, v216
	v_cmp_gt_f32_e32 vcc, 0x800000, v216
	s_nop 1
	v_cndmask_b32_e32 v216, v216, v119, vcc
	v_rsq_f32_e32 v216, v216
	s_nop 0
	v_mul_f32_e32 v119, 0x45800000, v216
	v_cndmask_b32_e32 v216, v216, v119, vcc
	v_pk_mul_f32 v[8:9], v[8:9], v[216:217] op_sel_hi:[1,0]
	v_pk_mul_f32 v[10:11], v[10:11], v[216:217] op_sel_hi:[1,0]
	v_pk_mul_f32 v[12:13], v[12:13], v[216:217] op_sel_hi:[1,0]
	v_pk_mul_f32 v[14:15], v[14:15], v[216:217] op_sel_hi:[1,0]
	v_pk_mul_f32 v[16:17], v[16:17], v[216:217] op_sel_hi:[1,0]
	v_pk_mul_f32 v[18:19], v[18:19], v[216:217] op_sel_hi:[1,0]
	v_pk_mul_f32 v[20:21], v[20:21], v[216:217] op_sel_hi:[1,0]
	v_pk_mul_f32 v[22:23], v[22:23], v[216:217] op_sel_hi:[1,0]
	v_pk_mul_f32 v[24:25], v[24:25], v[216:217] op_sel_hi:[1,0]
	v_pk_mul_f32 v[26:27], v[26:27], v[216:217] op_sel_hi:[1,0]
	v_pk_mul_f32 v[64:65], v[64:65], v[216:217] op_sel_hi:[1,0]
	v_pk_mul_f32 v[66:67], v[66:67], v[216:217] op_sel_hi:[1,0]
	v_pk_mul_f32 v[68:69], v[68:69], v[216:217] op_sel_hi:[1,0]
	v_pk_mul_f32 v[70:71], v[70:71], v[216:217] op_sel_hi:[1,0]
	v_pk_mul_f32 v[122:123], v[122:123], v[216:217] op_sel_hi:[1,0]
	v_pk_mul_f32 v[124:125], v[124:125], v[216:217] op_sel_hi:[1,0]
	v_mov_b32_e32 v218, 0
	v_cvt_pk_bf16_f32 v224, v8, v9
	v_cvt_pk_bf16_f32 v225, v10, v11
	v_cvt_pk_bf16_f32 v226, v12, v13
	v_cvt_pk_bf16_f32 v227, v14, v15
	v_xor_b32_e32 v119, 0, v113
	v_lshl_add_u32 v119, v119, 4, v111
	ds_write_b128 v119, v[224:227]
	v_pk_mul_f32 v[2:3], v[230:231], v[8:9] op_sel:[1,0] op_sel_hi:[1,1]
	v_cvt_pk_bf16_f32 v119, v2, v3
	global_store_short v115, v119, s[92:93] offset:0
	global_store_short_d16_hi v115, v119, s[92:93] offset:128
	v_pk_mul_f32 v[134:135], v[230:231], v[10:11] op_sel:[1,0] op_sel_hi:[1,1]
	v_cvt_pk_bf16_f32 v121, v134, v135
	global_store_short v115, v121, s[92:93] offset:256
	global_store_short_d16_hi v115, v121, s[92:93] offset:384
	v_pk_mul_f32 v[2:3], v[230:231], v[12:13] op_sel:[1,0] op_sel_hi:[1,1]
	v_cvt_pk_bf16_f32 v119, v2, v3
	global_store_short v115, v119, s[92:93] offset:512
	global_store_short_d16_hi v115, v119, s[92:93] offset:640
	v_pk_mul_f32 v[134:135], v[230:231], v[14:15] op_sel:[1,0] op_sel_hi:[1,1]
	v_cvt_pk_bf16_f32 v121, v134, v135
	global_store_short v115, v121, s[92:93] offset:768
	global_store_short_d16_hi v115, v121, s[92:93] offset:896
	v_cvt_pk_bf16_f32 v224, v16, v17
	v_cvt_pk_bf16_f32 v225, v18, v19
	v_cvt_pk_bf16_f32 v226, v20, v21
	v_cvt_pk_bf16_f32 v227, v22, v23
	v_xor_b32_e32 v119, 1, v113
	v_lshl_add_u32 v119, v119, 4, v111
	ds_write_b128 v119, v[224:227]
	v_pk_mul_f32 v[2:3], v[230:231], v[16:17] op_sel:[1,0] op_sel_hi:[1,1]
	v_cvt_pk_bf16_f32 v119, v2, v3
	global_store_short v115, v119, s[92:93] offset:1024
	global_store_short_d16_hi v115, v119, s[92:93] offset:1152
	v_pk_mul_f32 v[134:135], v[230:231], v[18:19] op_sel:[1,0] op_sel_hi:[1,1]
	v_cvt_pk_bf16_f32 v121, v134, v135
	global_store_short v115, v121, s[92:93] offset:1280
	global_store_short_d16_hi v115, v121, s[92:93] offset:1408
	v_pk_mul_f32 v[2:3], v[230:231], v[20:21] op_sel:[1,0] op_sel_hi:[1,1]
	v_cvt_pk_bf16_f32 v119, v2, v3
	global_store_short v115, v119, s[92:93] offset:1536
	global_store_short_d16_hi v115, v119, s[92:93] offset:1664
	v_pk_mul_f32 v[134:135], v[230:231], v[22:23] op_sel:[1,0] op_sel_hi:[1,1]
	v_cvt_pk_bf16_f32 v121, v134, v135
	global_store_short v115, v121, s[92:93] offset:1792
	global_store_short_d16_hi v115, v121, s[92:93] offset:1920
	v_cvt_pk_bf16_f32 v224, v24, v25
	v_cvt_pk_bf16_f32 v225, v26, v27
	v_cvt_pk_bf16_f32 v226, v64, v65
	v_cvt_pk_bf16_f32 v227, v66, v67
	v_xor_b32_e32 v119, 2, v113
	v_lshl_add_u32 v119, v119, 4, v111
	ds_write_b128 v119, v[224:227]
	v_pk_mul_f32 v[2:3], v[230:231], v[24:25] op_sel:[1,0] op_sel_hi:[1,1]
	v_cvt_pk_bf16_f32 v119, v2, v3
	global_store_short v115, v119, s[92:93] offset:2048
	global_store_short_d16_hi v115, v119, s[92:93] offset:2176
	v_pk_mul_f32 v[134:135], v[230:231], v[26:27] op_sel:[1,0] op_sel_hi:[1,1]
	v_cvt_pk_bf16_f32 v121, v134, v135
	global_store_short v115, v121, s[92:93] offset:2304
	global_store_short_d16_hi v115, v121, s[92:93] offset:2432
	v_pk_mul_f32 v[2:3], v[230:231], v[64:65] op_sel:[1,0] op_sel_hi:[1,1]
	v_cvt_pk_bf16_f32 v119, v2, v3
	global_store_short v115, v119, s[92:93] offset:2560
	global_store_short_d16_hi v115, v119, s[92:93] offset:2688
	v_pk_mul_f32 v[134:135], v[230:231], v[66:67] op_sel:[1,0] op_sel_hi:[1,1]
	v_cvt_pk_bf16_f32 v121, v134, v135
	global_store_short v115, v121, s[92:93] offset:2816
	global_store_short_d16_hi v115, v121, s[92:93] offset:2944
	v_cvt_pk_bf16_f32 v224, v68, v69
	v_cvt_pk_bf16_f32 v225, v70, v71
	v_cvt_pk_bf16_f32 v226, v122, v123
	v_cvt_pk_bf16_f32 v227, v124, v125
	v_xor_b32_e32 v119, 3, v113
	v_lshl_add_u32 v119, v119, 4, v111
	ds_write_b128 v119, v[224:227]
	v_pk_mul_f32 v[2:3], v[230:231], v[68:69] op_sel:[1,0] op_sel_hi:[1,1]
	v_cvt_pk_bf16_f32 v119, v2, v3
	global_store_short v115, v119, s[92:93] offset:3072
	global_store_short_d16_hi v115, v119, s[92:93] offset:3200
	v_pk_mul_f32 v[134:135], v[230:231], v[70:71] op_sel:[1,0] op_sel_hi:[1,1]
	v_cvt_pk_bf16_f32 v121, v134, v135
	global_store_short v115, v121, s[92:93] offset:3328
	global_store_short_d16_hi v115, v121, s[92:93] offset:3456
	v_pk_mul_f32 v[2:3], v[230:231], v[122:123] op_sel:[1,0] op_sel_hi:[1,1]
	v_cvt_pk_bf16_f32 v119, v2, v3
	global_store_short v115, v119, s[92:93] offset:3584
	global_store_short_d16_hi v115, v119, s[92:93] offset:3712
	v_pk_mul_f32 v[134:135], v[230:231], v[124:125] op_sel:[1,0] op_sel_hi:[1,1]
	v_cvt_pk_bf16_f32 v121, v134, v135
	global_store_short v115, v121, s[92:93] offset:3840
	global_store_short_d16_hi v115, v121, s[92:93] offset:3968
	s_cmp_lg_u32 s15, 0
	s_cbranch_scc1 .Lpb_sk_8
	s_waitcnt vmcnt(41)
	v_cndmask_b32_e64 v176, 0, v176, s[70:71]
	v_cndmask_b32_e64 v177, 0, v177, s[70:71]
	v_cndmask_b32_e64 v178, 0, v178, s[70:71]
	v_cndmask_b32_e64 v179, 0, v179, s[70:71]
	v_cndmask_b32_e64 v180, 0, v180, s[72:73]
	v_cndmask_b32_e64 v181, 0, v181, s[72:73]
	v_cndmask_b32_e64 v182, 0, v182, s[72:73]
	v_cndmask_b32_e64 v183, 0, v183, s[72:73]
	v_cndmask_b32_e64 v198, 0, v198, s[74:75]
	v_cndmask_b32_e64 v199, 0, v199, s[74:75]
	v_cndmask_b32_e64 v200, 0, v200, s[74:75]
	v_cndmask_b32_e64 v201, 0, v201, s[74:75]
.Lpb_sk_8:
	s_waitcnt vmcnt(43)
	v_lshlrev_b32_e32 v224, 16, v176
	v_and_b32_e32 v225, 0xffff0000, v176
	v_lshlrev_b32_e32 v226, 16, v177
	v_and_b32_e32 v227, 0xffff0000, v177
	s_waitcnt lgkmcnt(7)
	v_pk_fma_f32 v[126:127], v[48:49], v[224:225], 0 op_sel_hi:[1,1,0]
	v_pk_fma_f32 v[128:129], v[50:51], v[226:227], 0 op_sel_hi:[1,1,0]
	ds_read_b128 v[48:51], v255 offset:4608
	v_lshlrev_b32_e32 v224, 16, v178
	v_and_b32_e32 v225, 0xffff0000, v178
	v_lshlrev_b32_e32 v226, 16, v179
	v_and_b32_e32 v227, 0xffff0000, v179
	s_waitcnt lgkmcnt(7)
	v_pk_fma_f32 v[130:131], v[56:57], v[224:225], 0 op_sel_hi:[1,1,0]
	v_pk_fma_f32 v[132:133], v[58:59], v[226:227], 0 op_sel_hi:[1,1,0]
	ds_read_b128 v[56:59], v255 offset:4624
	global_load_dwordx4 v[176:179], v248, s[16:17] offset:2096
	s_waitcnt vmcnt(43)
	v_lshlrev_b32_e32 v224, 16, v180
	v_and_b32_e32 v225, 0xffff0000, v180
	v_lshlrev_b32_e32 v226, 16, v181
	v_and_b32_e32 v227, 0xffff0000, v181
	s_waitcnt lgkmcnt(7)
	v_pk_fma_f32 v[126:127], v[60:61], v[224:225], v[126:127]
	v_pk_fma_f32 v[128:129], v[62:63], v[226:227], v[128:129]
	ds_read_b128 v[60:63], v255 offset:6336
	v_lshlrev_b32_e32 v224, 16, v182
	v_and_b32_e32 v225, 0xffff0000, v182
	v_lshlrev_b32_e32 v226, 16, v183
	v_and_b32_e32 v227, 0xffff0000, v183
	s_waitcnt lgkmcnt(7)
	v_pk_fma_f32 v[130:131], v[220:221], v[224:225], v[130:131]
	v_pk_fma_f32 v[132:133], v[222:223], v[226:227], v[132:133]
	ds_read_b128 v[220:223], v255 offset:6352
	global_load_dwordx4 v[180:183], v249, s[16:17] offset:2096
	s_waitcnt vmcnt(43)
	v_lshlrev_b32_e32 v224, 16, v198
	v_and_b32_e32 v225, 0xffff0000, v198
	v_lshlrev_b32_e32 v226, 16, v199
	v_and_b32_e32 v227, 0xffff0000, v199
	s_waitcnt lgkmcnt(3)
	v_pk_fma_f32 v[126:127], v[48:49], v[224:225], v[126:127]
	v_pk_fma_f32 v[128:129], v[50:51], v[226:227], v[128:129]
	ds_read_b128 v[48:51], v255 offset:1184
	v_lshlrev_b32_e32 v224, 16, v200
	v_and_b32_e32 v225, 0xffff0000, v200
	v_lshlrev_b32_e32 v226, 16, v201
	v_and_b32_e32 v227, 0xffff0000, v201
	s_waitcnt lgkmcnt(3)
	v_pk_fma_f32 v[130:131], v[56:57], v[224:225], v[130:131]
	v_pk_fma_f32 v[132:133], v[58:59], v[226:227], v[132:133]
	ds_read_b128 v[56:59], v255 offset:1200
	global_load_dwordx4 v[198:201], v253, s[16:17] offset:2096
	s_waitcnt vmcnt(43)
	v_lshlrev_b32_e32 v224, 16, v210
	v_and_b32_e32 v225, 0xffff0000, v210
	v_lshlrev_b32_e32 v226, 16, v211
	v_and_b32_e32 v227, 0xffff0000, v211
	s_waitcnt lgkmcnt(3)
	v_pk_fma_f32 v[126:127], v[60:61], v[224:225], v[126:127]
	v_pk_fma_f32 v[128:129], v[62:63], v[226:227], v[128:129]
	ds_read_b128 v[60:63], v255 offset:2912
	v_lshlrev_b32_e32 v224, 16, v212
	v_and_b32_e32 v225, 0xffff0000, v212
	v_lshlrev_b32_e32 v226, 16, v213
	v_and_b32_e32 v227, 0xffff0000, v213
	s_waitcnt lgkmcnt(3)
	v_pk_fma_f32 v[130:131], v[220:221], v[224:225], v[130:131]
	v_pk_fma_f32 v[132:133], v[222:223], v[226:227], v[132:133]
	ds_read_b128 v[220:223], v255 offset:2928
	global_load_dwordx4 v[210:213], v254, s[16:17] offset:2096
	v_pk_mul_f32 v[224:225], v[126:127], s[18:19] op_sel_hi:[1,0]
	v_pk_mul_f32 v[226:227], v[128:129], s[18:19] op_sel_hi:[1,0]
	v_pk_mul_f32 v[2:3], v[130:131], s[18:19] op_sel_hi:[1,0]
	v_pk_mul_f32 v[134:135], v[132:133], s[18:19] op_sel_hi:[1,0]
	v_exp_f32_e32 v224, v224
	v_exp_f32_e32 v225, v225
	v_exp_f32_e32 v226, v226
	v_exp_f32_e32 v227, v227
	v_exp_f32_e32 v2, v2
	v_exp_f32_e32 v3, v3
	v_exp_f32_e32 v134, v134
	v_exp_f32_e32 v135, v135
	v_pk_add_f32 v[224:225], v[224:225], 1.0 op_sel_hi:[1,0]
	v_pk_add_f32 v[226:227], v[226:227], 1.0 op_sel_hi:[1,0]
	v_pk_add_f32 v[2:3], v[2:3], 1.0 op_sel_hi:[1,0]
	v_pk_add_f32 v[134:135], v[134:135], 1.0 op_sel_hi:[1,0]
	v_rcp_f32_e32 v224, v224
	v_rcp_f32_e32 v225, v225
	v_rcp_f32_e32 v226, v226
	v_rcp_f32_e32 v227, v227
	v_rcp_f32_e32 v2, v2
	v_rcp_f32_e32 v3, v3
	v_rcp_f32_e32 v134, v134
	v_rcp_f32_e32 v135, v135
	v_pk_mul_f32 v[8:9], v[126:127], v[224:225]
	v_pk_mul_f32 v[10:11], v[128:129], v[226:227]
	v_pk_mul_f32 v[12:13], v[130:131], v[2:3]
	v_pk_mul_f32 v[14:15], v[132:133], v[134:135]
	s_cmp_lg_u32 s15, 0
	s_cbranch_scc1 .Lpb_sk_9
	s_waitcnt vmcnt(41)
	v_cndmask_b32_e64 v28, 0, v28, s[70:71]
	v_cndmask_b32_e64 v29, 0, v29, s[70:71]
	v_cndmask_b32_e64 v30, 0, v30, s[70:71]
	v_cndmask_b32_e64 v31, 0, v31, s[70:71]
	v_cndmask_b32_e64 v32, 0, v32, s[72:73]
	v_cndmask_b32_e64 v33, 0, v33, s[72:73]
	v_cndmask_b32_e64 v34, 0, v34, s[72:73]
	v_cndmask_b32_e64 v35, 0, v35, s[72:73]
	v_cndmask_b32_e64 v36, 0, v36, s[74:75]
	v_cndmask_b32_e64 v37, 0, v37, s[74:75]
	v_cndmask_b32_e64 v38, 0, v38, s[74:75]
	v_cndmask_b32_e64 v39, 0, v39, s[74:75]
.Lpb_sk_9:
	s_waitcnt vmcnt(43)
	v_lshlrev_b32_e32 v224, 16, v28
	v_and_b32_e32 v225, 0xffff0000, v28
	v_lshlrev_b32_e32 v226, 16, v29
	v_and_b32_e32 v227, 0xffff0000, v29
	s_waitcnt lgkmcnt(3)
	v_pk_fma_f32 v[126:127], v[48:49], v[224:225], 0 op_sel_hi:[1,1,0]
	v_pk_fma_f32 v[128:129], v[50:51], v[226:227], 0 op_sel_hi:[1,1,0]
	ds_read_b128 v[48:51], v255 offset:4640
	v_lshlrev_b32_e32 v224, 16, v30
	v_and_b32_e32 v225, 0xffff0000, v30
	v_lshlrev_b32_e32 v226, 16, v31
	v_and_b32_e32 v227, 0xffff0000, v31
	s_waitcnt lgkmcnt(3)
	v_pk_fma_f32 v[130:131], v[56:57], v[224:225], 0 op_sel_hi:[1,1,0]
	v_pk_fma_f32 v[132:133], v[58:59], v[226:227], 0 op_sel_hi:[1,1,0]
	ds_read_b128 v[56:59], v255 offset:4656
	s_waitcnt vmcnt(42)
	v_lshlrev_b32_e32 v224, 16, v32
	v_and_b32_e32 v225, 0xffff0000, v32
	v_lshlrev_b32_e32 v226, 16, v33
	v_and_b32_e32 v227, 0xffff0000, v33
	s_waitcnt lgkmcnt(3)
	v_pk_fma_f32 v[126:127], v[60:61], v[224:225], v[126:127]
	v_pk_fma_f32 v[128:129], v[62:63], v[226:227], v[128:129]
	ds_read_b128 v[60:63], v255 offset:6368
	v_lshlrev_b32_e32 v224, 16, v34
	v_and_b32_e32 v225, 0xffff0000, v34
	v_lshlrev_b32_e32 v226, 16, v35
	v_and_b32_e32 v227, 0xffff0000, v35
	s_waitcnt lgkmcnt(3)
	v_pk_fma_f32 v[130:131], v[220:221], v[224:225], v[130:131]
	v_pk_fma_f32 v[132:133], v[222:223], v[226:227], v[132:133]
	ds_read_b128 v[220:223], v255 offset:6384
	s_waitcnt vmcnt(41)
	v_lshlrev_b32_e32 v224, 16, v36
	v_and_b32_e32 v225, 0xffff0000, v36
	v_lshlrev_b32_e32 v226, 16, v37
	v_and_b32_e32 v227, 0xffff0000, v37
	s_waitcnt lgkmcnt(3)
	v_pk_fma_f32 v[126:127], v[48:49], v[224:225], v[126:127]
	v_pk_fma_f32 v[128:129], v[50:51], v[226:227], v[128:129]
	ds_read_b128 v[48:51], v255 offset:1216
	v_lshlrev_b32_e32 v224, 16, v38
	v_and_b32_e32 v225, 0xffff0000, v38
	v_lshlrev_b32_e32 v226, 16, v39
	v_and_b32_e32 v227, 0xffff0000, v39
	s_waitcnt lgkmcnt(3)
	v_pk_fma_f32 v[130:131], v[56:57], v[224:225], v[130:131]
	v_pk_fma_f32 v[132:133], v[58:59], v[226:227], v[132:133]
	ds_read_b128 v[56:59], v255 offset:1232
	s_waitcnt vmcnt(40)
	v_lshlrev_b32_e32 v224, 16, v40
	v_and_b32_e32 v225, 0xffff0000, v40
	v_lshlrev_b32_e32 v226, 16, v41
	v_and_b32_e32 v227, 0xffff0000, v41
	s_waitcnt lgkmcnt(3)
	v_pk_fma_f32 v[126:127], v[60:61], v[224:225], v[126:127]
	v_pk_fma_f32 v[128:129], v[62:63], v[226:227], v[128:129]
	ds_read_b128 v[60:63], v255 offset:2944
	v_lshlrev_b32_e32 v224, 16, v42
	v_and_b32_e32 v225, 0xffff0000, v42
	v_lshlrev_b32_e32 v226, 16, v43
	v_and_b32_e32 v227, 0xffff0000, v43
	s_waitcnt lgkmcnt(3)
	v_pk_fma_f32 v[130:131], v[220:221], v[224:225], v[130:131]
	v_pk_fma_f32 v[132:133], v[222:223], v[226:227], v[132:133]
	ds_read_b128 v[220:223], v255 offset:2960
	v_pk_mul_f32 v[224:225], v[126:127], s[18:19] op_sel_hi:[1,0]
	v_pk_mul_f32 v[226:227], v[128:129], s[18:19] op_sel_hi:[1,0]
	v_pk_mul_f32 v[2:3], v[130:131], s[18:19] op_sel_hi:[1,0]
	v_pk_mul_f32 v[134:135], v[132:133], s[18:19] op_sel_hi:[1,0]
	v_exp_f32_e32 v224, v224
	v_exp_f32_e32 v225, v225
	v_exp_f32_e32 v226, v226
	v_exp_f32_e32 v227, v227
	v_exp_f32_e32 v2, v2
	v_exp_f32_e32 v3, v3
	v_exp_f32_e32 v134, v134
	v_exp_f32_e32 v135, v135
	v_pk_add_f32 v[224:225], v[224:225], 1.0 op_sel_hi:[1,0]
	v_pk_add_f32 v[226:227], v[226:227], 1.0 op_sel_hi:[1,0]
	v_pk_add_f32 v[2:3], v[2:3], 1.0 op_sel_hi:[1,0]
	v_pk_add_f32 v[134:135], v[134:135], 1.0 op_sel_hi:[1,0]
	v_rcp_f32_e32 v224, v224
	v_rcp_f32_e32 v225, v225
	v_rcp_f32_e32 v226, v226
	v_rcp_f32_e32 v227, v227
	v_rcp_f32_e32 v2, v2
	v_rcp_f32_e32 v3, v3
	v_rcp_f32_e32 v134, v134
	v_rcp_f32_e32 v135, v135
	v_pk_mul_f32 v[16:17], v[126:127], v[224:225]
	v_pk_mul_f32 v[18:19], v[128:129], v[226:227]
	v_pk_mul_f32 v[20:21], v[130:131], v[2:3]
	v_pk_mul_f32 v[22:23], v[132:133], v[134:135]
	s_cmp_lg_u32 s15, 0
	s_cbranch_scc1 .Lpb_sk_10
	s_waitcnt vmcnt(37)
	v_cndmask_b32_e64 v44, 0, v44, s[70:71]
	v_cndmask_b32_e64 v45, 0, v45, s[70:71]
	v_cndmask_b32_e64 v46, 0, v46, s[70:71]
	v_cndmask_b32_e64 v47, 0, v47, s[70:71]
	v_cndmask_b32_e64 v52, 0, v52, s[72:73]
	v_cndmask_b32_e64 v53, 0, v53, s[72:73]
	v_cndmask_b32_e64 v54, 0, v54, s[72:73]
	v_cndmask_b32_e64 v55, 0, v55, s[72:73]
	v_cndmask_b32_e64 v168, 0, v168, s[74:75]
	v_cndmask_b32_e64 v169, 0, v169, s[74:75]
	v_cndmask_b32_e64 v170, 0, v170, s[74:75]
	v_cndmask_b32_e64 v171, 0, v171, s[74:75]
.Lpb_sk_10:
	s_waitcnt vmcnt(39)
	v_lshlrev_b32_e32 v224, 16, v44
	v_and_b32_e32 v225, 0xffff0000, v44
	v_lshlrev_b32_e32 v226, 16, v45
	v_and_b32_e32 v227, 0xffff0000, v45
	s_waitcnt lgkmcnt(3)
	v_pk_fma_f32 v[126:127], v[48:49], v[224:225], 0 op_sel_hi:[1,1,0]
	v_pk_fma_f32 v[128:129], v[50:51], v[226:227], 0 op_sel_hi:[1,1,0]
	ds_read_b128 v[48:51], v255 offset:4672
	v_lshlrev_b32_e32 v224, 16, v46
	v_and_b32_e32 v225, 0xffff0000, v46
	v_lshlrev_b32_e32 v226, 16, v47
	v_and_b32_e32 v227, 0xffff0000, v47
	s_waitcnt lgkmcnt(3)
	v_pk_fma_f32 v[130:131], v[56:57], v[224:225], 0 op_sel_hi:[1,1,0]
	v_pk_fma_f32 v[132:133], v[58:59], v[226:227], 0 op_sel_hi:[1,1,0]
	ds_read_b128 v[56:59], v255 offset:4688
	s_waitcnt vmcnt(38)
	v_lshlrev_b32_e32 v224, 16, v52
	v_and_b32_e32 v225, 0xffff0000, v52
	v_lshlrev_b32_e32 v226, 16, v53
	v_and_b32_e32 v227, 0xffff0000, v53
	s_waitcnt lgkmcnt(3)
	v_pk_fma_f32 v[126:127], v[60:61], v[224:225], v[126:127]
	v_pk_fma_f32 v[128:129], v[62:63], v[226:227], v[128:129]
	ds_read_b128 v[60:63], v255 offset:6400
	v_lshlrev_b32_e32 v224, 16, v54
	v_and_b32_e32 v225, 0xffff0000, v54
	v_lshlrev_b32_e32 v226, 16, v55
	v_and_b32_e32 v227, 0xffff0000, v55
	s_waitcnt lgkmcnt(3)
	v_pk_fma_f32 v[130:131], v[220:221], v[224:225], v[130:131]
	v_pk_fma_f32 v[132:133], v[222:223], v[226:227], v[132:133]
	ds_read_b128 v[220:223], v255 offset:6416
	s_waitcnt vmcnt(37)
	v_lshlrev_b32_e32 v224, 16, v168
	v_and_b32_e32 v225, 0xffff0000, v168
	v_lshlrev_b32_e32 v226, 16, v169
	v_and_b32_e32 v227, 0xffff0000, v169
	s_waitcnt lgkmcnt(3)
	v_pk_fma_f32 v[126:127], v[48:49], v[224:225], v[126:127]
	v_pk_fma_f32 v[128:129], v[50:51], v[226:227], v[128:129]
	ds_read_b128 v[48:51], v255 offset:1248
	v_lshlrev_b32_e32 v224, 16, v170
	v_and_b32_e32 v225, 0xffff0000, v170
	v_lshlrev_b32_e32 v226, 16, v171
	v_and_b32_e32 v227, 0xffff0000, v171
	s_waitcnt lgkmcnt(3)
	v_pk_fma_f32 v[130:131], v[56:57], v[224:225], v[130:131]
	v_pk_fma_f32 v[132:133], v[58:59], v[226:227], v[132:133]
	ds_read_b128 v[56:59], v255 offset:1264
	s_waitcnt vmcnt(36)
	v_lshlrev_b32_e32 v224, 16, v172
	v_and_b32_e32 v225, 0xffff0000, v172
	v_lshlrev_b32_e32 v226, 16, v173
	v_and_b32_e32 v227, 0xffff0000, v173
	s_waitcnt lgkmcnt(3)
	v_pk_fma_f32 v[126:127], v[60:61], v[224:225], v[126:127]
	v_pk_fma_f32 v[128:129], v[62:63], v[226:227], v[128:129]
	ds_read_b128 v[60:63], v255 offset:2976
	v_lshlrev_b32_e32 v224, 16, v174
	v_and_b32_e32 v225, 0xffff0000, v174
	v_lshlrev_b32_e32 v226, 16, v175
	v_and_b32_e32 v227, 0xffff0000, v175
	s_waitcnt lgkmcnt(3)
	v_pk_fma_f32 v[130:131], v[220:221], v[224:225], v[130:131]
	v_pk_fma_f32 v[132:133], v[222:223], v[226:227], v[132:133]
	ds_read_b128 v[220:223], v255 offset:2992
	v_pk_mul_f32 v[224:225], v[126:127], s[18:19] op_sel_hi:[1,0]
	v_pk_mul_f32 v[226:227], v[128:129], s[18:19] op_sel_hi:[1,0]
	v_pk_mul_f32 v[2:3], v[130:131], s[18:19] op_sel_hi:[1,0]
	v_pk_mul_f32 v[134:135], v[132:133], s[18:19] op_sel_hi:[1,0]
	v_exp_f32_e32 v224, v224
	v_exp_f32_e32 v225, v225
	v_exp_f32_e32 v226, v226
	v_exp_f32_e32 v227, v227
	v_exp_f32_e32 v2, v2
	v_exp_f32_e32 v3, v3
	v_exp_f32_e32 v134, v134
	v_exp_f32_e32 v135, v135
	v_pk_add_f32 v[224:225], v[224:225], 1.0 op_sel_hi:[1,0]
	v_pk_add_f32 v[226:227], v[226:227], 1.0 op_sel_hi:[1,0]
	v_pk_add_f32 v[2:3], v[2:3], 1.0 op_sel_hi:[1,0]
	v_pk_add_f32 v[134:135], v[134:135], 1.0 op_sel_hi:[1,0]
	v_rcp_f32_e32 v224, v224
	v_rcp_f32_e32 v225, v225
	v_rcp_f32_e32 v226, v226
	v_rcp_f32_e32 v227, v227
	v_rcp_f32_e32 v2, v2
	v_rcp_f32_e32 v3, v3
	v_rcp_f32_e32 v134, v134
	v_rcp_f32_e32 v135, v135
	v_pk_mul_f32 v[24:25], v[126:127], v[224:225]
	v_pk_mul_f32 v[26:27], v[128:129], v[226:227]
	v_pk_mul_f32 v[64:65], v[130:131], v[2:3]
	v_pk_mul_f32 v[66:67], v[132:133], v[134:135]
	s_cmp_lg_u32 s15, 0
	s_cbranch_scc1 .Lpb_sk_11
	s_waitcnt vmcnt(1)
	v_cndmask_b32_e64 v176, 0, v176, s[70:71]
	v_cndmask_b32_e64 v177, 0, v177, s[70:71]
	v_cndmask_b32_e64 v178, 0, v178, s[70:71]
	v_cndmask_b32_e64 v179, 0, v179, s[70:71]
	v_cndmask_b32_e64 v180, 0, v180, s[72:73]
	v_cndmask_b32_e64 v181, 0, v181, s[72:73]
	v_cndmask_b32_e64 v182, 0, v182, s[72:73]
	v_cndmask_b32_e64 v183, 0, v183, s[72:73]
	v_cndmask_b32_e64 v198, 0, v198, s[74:75]
	v_cndmask_b32_e64 v199, 0, v199, s[74:75]
	v_cndmask_b32_e64 v200, 0, v200, s[74:75]
	v_cndmask_b32_e64 v201, 0, v201, s[74:75]
.Lpb_sk_11:
	s_waitcnt vmcnt(3)
	v_lshlrev_b32_e32 v224, 16, v176
	v_and_b32_e32 v225, 0xffff0000, v176
	v_lshlrev_b32_e32 v226, 16, v177
	v_and_b32_e32 v227, 0xffff0000, v177
	s_waitcnt lgkmcnt(3)
	v_pk_fma_f32 v[126:127], v[48:49], v[224:225], 0 op_sel_hi:[1,1,0]
	v_pk_fma_f32 v[128:129], v[50:51], v[226:227], 0 op_sel_hi:[1,1,0]
	ds_read_b128 v[48:51], v255 offset:4704
	v_lshlrev_b32_e32 v224, 16, v178
	v_and_b32_e32 v225, 0xffff0000, v178
	v_lshlrev_b32_e32 v226, 16, v179
	v_and_b32_e32 v227, 0xffff0000, v179
	s_waitcnt lgkmcnt(3)
	v_pk_fma_f32 v[130:131], v[56:57], v[224:225], 0 op_sel_hi:[1,1,0]
	v_pk_fma_f32 v[132:133], v[58:59], v[226:227], 0 op_sel_hi:[1,1,0]
	ds_read_b128 v[56:59], v255 offset:4720
	s_waitcnt vmcnt(2)
	v_lshlrev_b32_e32 v224, 16, v180
	v_and_b32_e32 v225, 0xffff0000, v180
	v_lshlrev_b32_e32 v226, 16, v181
	v_and_b32_e32 v227, 0xffff0000, v181
	s_waitcnt lgkmcnt(3)
	v_pk_fma_f32 v[126:127], v[60:61], v[224:225], v[126:127]
	v_pk_fma_f32 v[128:129], v[62:63], v[226:227], v[128:129]
	ds_read_b128 v[60:63], v255 offset:6432
	v_lshlrev_b32_e32 v224, 16, v182
	v_and_b32_e32 v225, 0xffff0000, v182
	v_lshlrev_b32_e32 v226, 16, v183
	v_and_b32_e32 v227, 0xffff0000, v183
	s_waitcnt lgkmcnt(3)
	v_pk_fma_f32 v[130:131], v[220:221], v[224:225], v[130:131]
	v_pk_fma_f32 v[132:133], v[222:223], v[226:227], v[132:133]
	ds_read_b128 v[220:223], v255 offset:6448
	s_waitcnt vmcnt(1)
	v_lshlrev_b32_e32 v224, 16, v198
	v_and_b32_e32 v225, 0xffff0000, v198
	v_lshlrev_b32_e32 v226, 16, v199
	v_and_b32_e32 v227, 0xffff0000, v199
	s_waitcnt lgkmcnt(3)
	v_pk_fma_f32 v[126:127], v[48:49], v[224:225], v[126:127]
	v_pk_fma_f32 v[128:129], v[50:51], v[226:227], v[128:129]
	v_lshlrev_b32_e32 v224, 16, v200
	v_and_b32_e32 v225, 0xffff0000, v200
	v_lshlrev_b32_e32 v226, 16, v201
	v_and_b32_e32 v227, 0xffff0000, v201
	s_waitcnt lgkmcnt(2)
	v_pk_fma_f32 v[130:131], v[56:57], v[224:225], v[130:131]
	v_pk_fma_f32 v[132:133], v[58:59], v[226:227], v[132:133]
	s_waitcnt vmcnt(0)
	v_lshlrev_b32_e32 v224, 16, v210
	v_and_b32_e32 v225, 0xffff0000, v210
	v_lshlrev_b32_e32 v226, 16, v211
	v_and_b32_e32 v227, 0xffff0000, v211
	s_waitcnt lgkmcnt(1)
	v_pk_fma_f32 v[126:127], v[60:61], v[224:225], v[126:127]
	v_pk_fma_f32 v[128:129], v[62:63], v[226:227], v[128:129]
	v_lshlrev_b32_e32 v224, 16, v212
	v_and_b32_e32 v225, 0xffff0000, v212
	v_lshlrev_b32_e32 v226, 16, v213
	v_and_b32_e32 v227, 0xffff0000, v213
	s_waitcnt lgkmcnt(0)
	v_pk_fma_f32 v[130:131], v[220:221], v[224:225], v[130:131]
	v_pk_fma_f32 v[132:133], v[222:223], v[226:227], v[132:133]
	v_pk_mul_f32 v[224:225], v[126:127], s[18:19] op_sel_hi:[1,0]
	v_pk_mul_f32 v[226:227], v[128:129], s[18:19] op_sel_hi:[1,0]
	v_pk_mul_f32 v[2:3], v[130:131], s[18:19] op_sel_hi:[1,0]
	v_pk_mul_f32 v[134:135], v[132:133], s[18:19] op_sel_hi:[1,0]
	v_exp_f32_e32 v224, v224
	v_exp_f32_e32 v225, v225
	v_exp_f32_e32 v226, v226
	v_exp_f32_e32 v227, v227
	v_exp_f32_e32 v2, v2
	v_exp_f32_e32 v3, v3
	v_exp_f32_e32 v134, v134
	v_exp_f32_e32 v135, v135
	v_pk_add_f32 v[224:225], v[224:225], 1.0 op_sel_hi:[1,0]
	v_pk_add_f32 v[226:227], v[226:227], 1.0 op_sel_hi:[1,0]
	v_pk_add_f32 v[2:3], v[2:3], 1.0 op_sel_hi:[1,0]
	v_pk_add_f32 v[134:135], v[134:135], 1.0 op_sel_hi:[1,0]
	v_rcp_f32_e32 v224, v224
	v_rcp_f32_e32 v225, v225
	v_rcp_f32_e32 v226, v226
	v_rcp_f32_e32 v227, v227
	v_rcp_f32_e32 v2, v2
	v_rcp_f32_e32 v3, v3
	v_rcp_f32_e32 v134, v134
	v_rcp_f32_e32 v135, v135
	v_pk_mul_f32 v[68:69], v[126:127], v[224:225]
	v_pk_mul_f32 v[70:71], v[128:129], v[226:227]
	v_pk_mul_f32 v[122:123], v[130:131], v[2:3]
	v_pk_mul_f32 v[124:125], v[132:133], v[134:135]
	v_cvt_pk_bf16_f32 v224, v8, v9
	v_cvt_pk_bf16_f32 v225, v10, v11
	v_cvt_pk_bf16_f32 v226, v12, v13
	v_cvt_pk_bf16_f32 v227, v14, v15
	ds_write_b128 v117, v[224:227] offset:0
	v_cvt_pk_bf16_f32 v224, v16, v17
	v_cvt_pk_bf16_f32 v225, v18, v19
	v_cvt_pk_bf16_f32 v226, v20, v21
	v_cvt_pk_bf16_f32 v227, v22, v23
	ds_write_b128 v117, v[224:227] offset:16
	v_cvt_pk_bf16_f32 v224, v24, v25
	v_cvt_pk_bf16_f32 v225, v26, v27
	v_cvt_pk_bf16_f32 v226, v64, v65
	v_cvt_pk_bf16_f32 v227, v66, v67
	ds_write_b128 v117, v[224:227] offset:32
	v_cvt_pk_bf16_f32 v224, v68, v69
	v_cvt_pk_bf16_f32 v225, v70, v71
	v_cvt_pk_bf16_f32 v226, v122, v123
	v_cvt_pk_bf16_f32 v227, v124, v125
	ds_write_b128 v117, v[224:227] offset:48
	v_add_u32_e32 v111, v151, v149
	v_add_u32_e32 v0, v151, v143
	v_readlane_b32 s12, v252, 32
	v_readlane_b32 s13, v252, 33
	s_waitcnt lgkmcnt(0)
	s_barrier
	ds_read_b128 v[64:67], v144
	ds_read_b128 v[68:71], v144 offset:16384
	ds_read_b128 v[56:59], v146
	ds_read_b128 v[60:63], v146 offset:16384
	ds_read_b128 v[48:51], v148
	ds_read_b128 v[52:55], v148 offset:16384
	ds_read_b128 v[40:43], v150
	ds_read_b128 v[44:47], v150 offset:16384
	ds_read_b128 v[8:11], v0
	v_add_u32_e32 v2, v151, v145
	ds_read_b128 v[16:19], v2
	s_waitcnt lgkmcnt(1)
	v_mfma_f32_16x16x32_bf16 v[12:15], v[64:67], v[8:11], 0
	v_add_u32_e32 v3, v151, v147
	v_mov_b32_e32 v28, 0
	v_mov_b32_e32 v29, 0
	v_mfma_f32_16x16x32_bf16 v[8:11], v[68:71], v[8:11], 0
	v_mov_b32_e32 v30, 0
	v_mov_b32_e32 v31, 0
	v_mov_b32_e32 v24, 0
	s_waitcnt lgkmcnt(0)
	v_mfma_f32_16x16x32_bf16 v[12:15], v[56:59], v[16:19], v[12:15]
	v_mov_b32_e32 v25, 0
	v_mov_b32_e32 v26, 0
	v_mov_b32_e32 v27, 0
	v_mfma_f32_16x16x32_bf16 v[8:11], v[60:63], v[16:19], v[8:11]
	ds_read_b128 v[16:19], v3
	s_waitcnt lgkmcnt(0)
	v_mfma_f32_16x16x32_bf16 v[12:15], v[48:51], v[16:19], v[12:15]
	v_mfma_f32_16x16x32_bf16 v[8:11], v[52:55], v[16:19], v[8:11]
	ds_read_b128 v[16:19], v111
	s_waitcnt lgkmcnt(0)
	v_mfma_f32_16x16x32_bf16 v[36:39], v[40:43], v[16:19], v[12:15]
	v_mfma_f32_16x16x32_bf16 v[32:35], v[44:47], v[16:19], v[8:11]
	s_nop 3
	v_mov_b32_e32 v8, 0
	s_and_saveexec_b64 s[0:1], s[12:13]
	s_cbranch_execz .LBB0_273
	ds_read_b128 v[10:13], v0 offset:4096
	ds_read_b128 v[18:21], v2 offset:4096
	s_waitcnt lgkmcnt(1)
	v_mfma_f32_16x16x32_bf16 v[14:17], v[64:67], v[10:13], 0
	v_mfma_f32_16x16x32_bf16 v[10:13], v[68:71], v[10:13], 0
	s_waitcnt lgkmcnt(0)
	v_mfma_f32_16x16x32_bf16 v[14:17], v[56:59], v[18:21], v[14:17]
	v_mfma_f32_16x16x32_bf16 v[10:13], v[60:63], v[18:21], v[10:13]
	ds_read_b128 v[18:21], v3 offset:4096
	s_waitcnt lgkmcnt(0)
	v_mfma_f32_16x16x32_bf16 v[14:17], v[48:51], v[18:21], v[14:17]
	v_mfma_f32_16x16x32_bf16 v[10:13], v[52:55], v[18:21], v[10:13]
	ds_read_b128 v[18:21], v111 offset:4096
	s_waitcnt lgkmcnt(0)
	v_mfma_f32_16x16x32_bf16 v[28:31], v[40:43], v[18:21], v[14:17]
	v_mfma_f32_16x16x32_bf16 v[24:27], v[44:47], v[18:21], v[10:13]
